# kv/q up-projection epilogues: row statistic and position loads hoisted out of the store ladders; final norm gain hoisted
# baseline (speedup 1.0000x reference)
.LBB0_394:
	v_mov_b32_e32 v129, v198
	s_movk_i32 s6, 0x1f8f
	v_ashrrev_i32_e32 v128, 1, v129
	v_and_b32_e32 v128, 0xffffff80, v128
	v_and_b32_e32 v132, 15, v129
	v_lshl_add_u32 v133, v149, 8, v128
	v_or_b32_e32 v128, v133, v132
	v_lshlrev_b32_e32 v130, 1, v128
	v_ashrrev_i32_e32 v131, 31, v130
	v_lshl_add_u64 v[130:131], v[130:131], 2, s[62:63]
	v_add_co_u32_e32 v130, vcc, s82, v130
	s_nop 1
	v_addc_co_u32_e32 v131, vcc, 0, v131, vcc
	global_load_dword v134, v[130:131], off offset:4
	global_load_dword v242, v[130:131], off offset:132
	global_load_dword v243, v[130:131], off offset:260
	global_load_dword v244, v[130:131], off offset:388
	global_load_dword v245, v[130:131], off offset:516
	global_load_dword v246, v[130:131], off offset:644
	global_load_dword v247, v[130:131], off offset:772
	global_load_dword v248, v[130:131], off offset:900
	v_lshlrev_b32_e32 v130, 8, v148
	v_and_or_b32 v168, v129, s61, v130
	v_lshrrev_b32_e32 v130, 1, v129
	v_and_b32_e32 v129, 64, v129
	v_lshrrev_b32_e32 v135, 7, v168
	v_and_b32_e32 v162, 24, v130
	v_cmp_ne_u32_e64 s[2:3], 0, v129
	v_ashrrev_i32_e32 v129, 10, v133
	v_bitop3_b32 v130, v133, s6, v132 bitop3:0xc8
	s_mov_b32 s6, 0x3fffff8
	v_and_or_b32 v129, v129, s6, v135
	v_mov_b32_e32 v131, v169
	v_lshlrev_b32_e32 v130, 1, v130
	v_lshlrev_b32_e32 v163, 6, v129
	v_lshl_add_u64 v[150:151], s[16:17], 0, v[130:131]
	v_or_b32_e32 v142, v163, v162
	v_ashrrev_i32_e32 v143, 31, v142
	v_or_b32_e32 v140, 4, v142
	v_or_b32_e32 v138, 1, v142
	v_or_b32_e32 v136, 5, v142
	v_or_b32_e32 v132, 6, v142
	s_waitcnt vmcnt(0)
	v_fmamk_f32 v129, v134, 0x3b800000, v174
	v_mul_f32_e32 v130, 0x4b800000, v129
	v_cmp_gt_f32_e32 vcc, s83, v129
	v_or_b32_e32 v134, 2, v142
	s_nop 0
	v_cndmask_b32_e32 v129, v129, v130, vcc
	v_rsq_f32_e32 v129, v129
	v_or_b32_e32 v130, 3, v142
	v_mul_f32_e32 v131, 0x45800000, v129
	v_cndmask_b32_e32 v144, v129, v131, vcc
	v_pk_mul_f32 v[126:127], v[126:127], v[144:145] op_sel_hi:[1,0]
	v_pk_mul_f32 v[152:153], v[124:125], v[144:145] op_sel_hi:[1,0]
	v_pk_mul_f32 v[124:125], v[122:123], v[144:145] op_sel_hi:[1,0]
	v_pk_mul_f32 v[146:147], v[120:121], v[144:145] op_sel_hi:[1,0]
	v_or_b32_e32 v120, 7, v142
	s_and_saveexec_b64 s[6:7], s[2:3]
	s_xor_b64 s[6:7], exec, s[6:7]
	s_cbranch_execz .LBB0_396
	v_lshlrev_b64 v[122:123], 14, v[142:143]
	v_cvt_pk_bf16_f32 v121, v152, s0
	v_lshl_add_u64 v[122:123], v[150:151], 0, v[122:123]
	v_ashrrev_i32_e32 v141, 31, v140
	global_store_short v[122:123], v121, off
	v_lshlrev_b64 v[122:123], 14, v[140:141]
	v_cvt_pk_bf16_f32 v121, v146, s0
	v_lshl_add_u64 v[122:123], v[150:151], 0, v[122:123]
	v_ashrrev_i32_e32 v139, 31, v138
	global_store_short v[122:123], v121, off
	v_lshlrev_b64 v[122:123], 14, v[138:139]
	v_cvt_pk_bf16_f32 v121, v153, s0
	v_lshl_add_u64 v[122:123], v[150:151], 0, v[122:123]
	v_ashrrev_i32_e32 v137, 31, v136
	global_store_short v[122:123], v121, off
	v_lshlrev_b64 v[122:123], 14, v[136:137]
	v_cvt_pk_bf16_f32 v121, v147, s0
	v_lshl_add_u64 v[122:123], v[150:151], 0, v[122:123]
	v_ashrrev_i32_e32 v135, 31, v134
	global_store_short v[122:123], v121, off
	v_lshlrev_b64 v[122:123], 14, v[134:135]
	v_cvt_pk_bf16_f32 v121, v126, s0
	v_lshl_add_u64 v[122:123], v[150:151], 0, v[122:123]
	v_ashrrev_i32_e32 v133, 31, v132
	global_store_short v[122:123], v121, off
	v_lshlrev_b64 v[122:123], 14, v[132:133]
	v_cvt_pk_bf16_f32 v121, v124, s0
	v_lshl_add_u64 v[122:123], v[150:151], 0, v[122:123]
	v_ashrrev_i32_e32 v131, 31, v130
	global_store_short v[122:123], v121, off
	v_lshlrev_b64 v[122:123], 14, v[130:131]
	v_cvt_pk_bf16_f32 v121, v127, s0
	v_lshl_add_u64 v[122:123], v[150:151], 0, v[122:123]
	global_store_short v[122:123], v121, off
	v_ashrrev_i32_e32 v121, 31, v120
	v_lshlrev_b64 v[122:123], 14, v[120:121]
	v_cvt_pk_bf16_f32 v124, v125, s0
	v_lshl_add_u64 v[122:123], v[150:151], 0, v[122:123]
	global_store_short v[122:123], v124, off

.LBB0_402:
	s_or_b64 exec, exec, s[6:7]
	v_or_b32_e32 v152, 16, v128
	v_lshlrev_b32_e32 v150, 1, v152
	v_ashrrev_i32_e32 v151, 31, v150
	v_lshl_add_u64 v[150:151], v[150:151], 2, s[62:63]
	v_add_co_u32_e32 v150, vcc, 0xe000, v150
	s_movk_i32 s6, 0x1f9f
	s_nop 0
	v_addc_co_u32_e32 v151, vcc, 0, v151, vcc
	s_nop 1
	v_mov_b32_e32 v113, v242
	v_fmamk_f32 v113, v113, 0x3b800000, v174
	v_mul_f32_e32 v115, 0x4b800000, v113
	v_cmp_gt_f32_e32 vcc, s83, v113
	s_nop 1
	v_cndmask_b32_e32 v113, v113, v115, vcc
	v_rsq_f32_e32 v113, v113
	v_bitop3_b32 v115, v128, s6, 16 bitop3:0xc8
	v_lshlrev_b32_e32 v168, 1, v115
	v_lshl_add_u64 v[150:151], s[16:17], 0, v[168:169]
	v_mul_f32_e32 v115, 0x45800000, v113
	v_cndmask_b32_e32 v154, v113, v115, vcc
	v_pk_mul_f32 v[110:111], v[110:111], v[154:155] op_sel_hi:[1,0]
	v_pk_mul_f32 v[156:157], v[108:109], v[154:155] op_sel_hi:[1,0]
	v_pk_mul_f32 v[106:107], v[106:107], v[154:155] op_sel_hi:[1,0]
	v_pk_mul_f32 v[108:109], v[104:105], v[154:155] op_sel_hi:[1,0]
	s_and_saveexec_b64 s[6:7], s[2:3]
	s_xor_b64 s[6:7], exec, s[6:7]
	s_cbranch_execz .LBB0_404
	v_lshlrev_b64 v[104:105], 14, v[142:143]
	v_cvt_pk_bf16_f32 v113, v156, s0
	v_lshl_add_u64 v[104:105], v[150:151], 0, v[104:105]
	v_ashrrev_i32_e32 v141, 31, v140
	global_store_short v[104:105], v113, off
	v_lshlrev_b64 v[104:105], 14, v[140:141]
	v_cvt_pk_bf16_f32 v108, v108, s0
	v_lshl_add_u64 v[104:105], v[150:151], 0, v[104:105]
	v_ashrrev_i32_e32 v139, 31, v138
	global_store_short v[104:105], v108, off
	v_lshlrev_b64 v[104:105], 14, v[138:139]
	v_cvt_pk_bf16_f32 v108, v157, s0
	v_lshl_add_u64 v[104:105], v[150:151], 0, v[104:105]
	v_ashrrev_i32_e32 v137, 31, v136
	global_store_short v[104:105], v108, off
	v_lshlrev_b64 v[104:105], 14, v[136:137]
	v_cvt_pk_bf16_f32 v108, v109, s0
	v_lshl_add_u64 v[104:105], v[150:151], 0, v[104:105]
	v_ashrrev_i32_e32 v135, 31, v134
	global_store_short v[104:105], v108, off
	v_lshlrev_b64 v[104:105], 14, v[134:135]
	v_cvt_pk_bf16_f32 v108, v110, s0
	v_lshl_add_u64 v[104:105], v[150:151], 0, v[104:105]
	v_ashrrev_i32_e32 v133, 31, v132
	global_store_short v[104:105], v108, off
	v_lshlrev_b64 v[104:105], 14, v[132:133]
	v_cvt_pk_bf16_f32 v106, v106, s0
	v_lshl_add_u64 v[104:105], v[150:151], 0, v[104:105]
	v_ashrrev_i32_e32 v131, 31, v130
	global_store_short v[104:105], v106, off
	v_lshlrev_b64 v[104:105], 14, v[130:131]
	v_cvt_pk_bf16_f32 v106, v111, s0
	v_lshl_add_u64 v[104:105], v[150:151], 0, v[104:105]
	v_ashrrev_i32_e32 v121, 31, v120
	global_store_short v[104:105], v106, off
	v_lshlrev_b64 v[104:105], 14, v[120:121]
	v_cvt_pk_bf16_f32 v106, v107, s0
	v_lshl_add_u64 v[104:105], v[150:151], 0, v[104:105]
	global_store_short v[104:105], v106, off

.LBB0_410:
	s_or_b64 exec, exec, s[6:7]
	v_or_b32_e32 v98, 32, v128
	v_lshlrev_b32_e32 v96, 1, v98
	v_ashrrev_i32_e32 v97, 31, v96
	v_lshl_add_u64 v[96:97], v[96:97], 2, s[62:63]
	v_add_co_u32_e32 v96, vcc, 0xe000, v96
	s_movk_i32 s6, 0x1faf
	s_nop 0
	v_addc_co_u32_e32 v97, vcc, 0, v97, vcc
	s_nop 1
	v_mov_b32_e32 v96, v243
	v_fmamk_f32 v96, v96, 0x3b800000, v174
	v_mul_f32_e32 v97, 0x4b800000, v96
	v_cmp_gt_f32_e32 vcc, s83, v96
	s_nop 1
	v_cndmask_b32_e32 v96, v96, v97, vcc
	v_rsq_f32_e32 v99, v96
	v_bitop3_b32 v96, v128, s6, 32 bitop3:0xc8
	v_lshlrev_b32_e32 v168, 1, v96
	v_lshl_add_u64 v[96:97], s[16:17], 0, v[168:169]
	v_mul_f32_e32 v100, 0x45800000, v99
	v_cndmask_b32_e32 v100, v99, v100, vcc
	v_pk_mul_f32 v[94:95], v[94:95], v[100:101] op_sel_hi:[1,0]
	v_pk_mul_f32 v[102:103], v[92:93], v[100:101] op_sel_hi:[1,0]
	v_pk_mul_f32 v[90:91], v[90:91], v[100:101] op_sel_hi:[1,0]
	v_pk_mul_f32 v[92:93], v[88:89], v[100:101] op_sel_hi:[1,0]
	s_and_saveexec_b64 s[6:7], s[2:3]
	s_xor_b64 s[6:7], exec, s[6:7]
	s_cbranch_execz .LBB0_412
	v_lshlrev_b64 v[88:89], 14, v[142:143]
	v_cvt_pk_bf16_f32 v99, v102, s0
	v_lshl_add_u64 v[88:89], v[96:97], 0, v[88:89]
	v_ashrrev_i32_e32 v141, 31, v140
	global_store_short v[88:89], v99, off
	v_lshlrev_b64 v[88:89], 14, v[140:141]
	v_cvt_pk_bf16_f32 v92, v92, s0
	v_lshl_add_u64 v[88:89], v[96:97], 0, v[88:89]
	v_ashrrev_i32_e32 v139, 31, v138
	global_store_short v[88:89], v92, off
	v_lshlrev_b64 v[88:89], 14, v[138:139]
	v_cvt_pk_bf16_f32 v92, v103, s0
	v_lshl_add_u64 v[88:89], v[96:97], 0, v[88:89]
	v_ashrrev_i32_e32 v137, 31, v136
	global_store_short v[88:89], v92, off
	v_lshlrev_b64 v[88:89], 14, v[136:137]
	v_cvt_pk_bf16_f32 v92, v93, s0
	v_lshl_add_u64 v[88:89], v[96:97], 0, v[88:89]
	v_ashrrev_i32_e32 v135, 31, v134
	global_store_short v[88:89], v92, off
	v_lshlrev_b64 v[88:89], 14, v[134:135]
	v_cvt_pk_bf16_f32 v92, v94, s0
	v_lshl_add_u64 v[88:89], v[96:97], 0, v[88:89]
	v_ashrrev_i32_e32 v133, 31, v132
	global_store_short v[88:89], v92, off
	v_lshlrev_b64 v[88:89], 14, v[132:133]
	v_cvt_pk_bf16_f32 v90, v90, s0
	v_lshl_add_u64 v[88:89], v[96:97], 0, v[88:89]
	v_ashrrev_i32_e32 v131, 31, v130
	global_store_short v[88:89], v90, off
	v_lshlrev_b64 v[88:89], 14, v[130:131]
	v_cvt_pk_bf16_f32 v90, v95, s0
	v_lshl_add_u64 v[88:89], v[96:97], 0, v[88:89]
	v_ashrrev_i32_e32 v121, 31, v120
	global_store_short v[88:89], v90, off
	v_lshlrev_b64 v[88:89], 14, v[120:121]
	v_cvt_pk_bf16_f32 v90, v91, s0
	v_lshl_add_u64 v[88:89], v[96:97], 0, v[88:89]
	global_store_short v[88:89], v90, off

.LBB0_418:
	s_or_b64 exec, exec, s[6:7]
	v_or_b32_e32 v82, 48, v128
	v_lshlrev_b32_e32 v80, 1, v82
	v_ashrrev_i32_e32 v81, 31, v80
	v_lshl_add_u64 v[80:81], v[80:81], 2, s[62:63]
	v_add_co_u32_e32 v80, vcc, 0xe000, v80
	s_movk_i32 s6, 0x1fbf
	s_nop 0
	v_addc_co_u32_e32 v81, vcc, 0, v81, vcc
	s_nop 1
	v_mov_b32_e32 v80, v244
	v_fmamk_f32 v80, v80, 0x3b800000, v174
	v_mul_f32_e32 v81, 0x4b800000, v80
	v_cmp_gt_f32_e32 vcc, s83, v80
	s_nop 1
	v_cndmask_b32_e32 v80, v80, v81, vcc
	v_rsq_f32_e32 v83, v80
	v_bitop3_b32 v80, v128, s6, 48 bitop3:0xc8
	v_lshlrev_b32_e32 v168, 1, v80
	v_lshl_add_u64 v[80:81], s[16:17], 0, v[168:169]
	v_mul_f32_e32 v84, 0x45800000, v83
	v_cndmask_b32_e32 v84, v83, v84, vcc
	v_pk_mul_f32 v[78:79], v[78:79], v[84:85] op_sel_hi:[1,0]
	v_pk_mul_f32 v[86:87], v[76:77], v[84:85] op_sel_hi:[1,0]
	v_pk_mul_f32 v[74:75], v[74:75], v[84:85] op_sel_hi:[1,0]
	v_pk_mul_f32 v[76:77], v[72:73], v[84:85] op_sel_hi:[1,0]
	s_and_saveexec_b64 s[6:7], s[2:3]
	s_xor_b64 s[6:7], exec, s[6:7]
	s_cbranch_execz .LBB0_420
	v_lshlrev_b64 v[72:73], 14, v[142:143]
	v_cvt_pk_bf16_f32 v83, v86, s0
	v_lshl_add_u64 v[72:73], v[80:81], 0, v[72:73]
	v_ashrrev_i32_e32 v141, 31, v140
	global_store_short v[72:73], v83, off
	v_lshlrev_b64 v[72:73], 14, v[140:141]
	v_cvt_pk_bf16_f32 v76, v76, s0
	v_lshl_add_u64 v[72:73], v[80:81], 0, v[72:73]
	v_ashrrev_i32_e32 v139, 31, v138
	global_store_short v[72:73], v76, off
	v_lshlrev_b64 v[72:73], 14, v[138:139]
	v_cvt_pk_bf16_f32 v76, v87, s0
	v_lshl_add_u64 v[72:73], v[80:81], 0, v[72:73]
	v_ashrrev_i32_e32 v137, 31, v136
	global_store_short v[72:73], v76, off
	v_lshlrev_b64 v[72:73], 14, v[136:137]
	v_cvt_pk_bf16_f32 v76, v77, s0
	v_lshl_add_u64 v[72:73], v[80:81], 0, v[72:73]
	v_ashrrev_i32_e32 v135, 31, v134
	global_store_short v[72:73], v76, off
	v_lshlrev_b64 v[72:73], 14, v[134:135]
	v_cvt_pk_bf16_f32 v76, v78, s0
	v_lshl_add_u64 v[72:73], v[80:81], 0, v[72:73]
	v_ashrrev_i32_e32 v133, 31, v132
	global_store_short v[72:73], v76, off
	v_lshlrev_b64 v[72:73], 14, v[132:133]
	v_cvt_pk_bf16_f32 v74, v74, s0
	v_lshl_add_u64 v[72:73], v[80:81], 0, v[72:73]
	v_ashrrev_i32_e32 v131, 31, v130
	global_store_short v[72:73], v74, off
	v_lshlrev_b64 v[72:73], 14, v[130:131]
	v_cvt_pk_bf16_f32 v74, v79, s0
	v_lshl_add_u64 v[72:73], v[80:81], 0, v[72:73]
	v_ashrrev_i32_e32 v121, 31, v120
	global_store_short v[72:73], v74, off
	v_lshlrev_b64 v[72:73], 14, v[120:121]
	v_cvt_pk_bf16_f32 v74, v75, s0
	v_lshl_add_u64 v[72:73], v[80:81], 0, v[72:73]
	global_store_short v[72:73], v74, off

.LBB0_426:
	s_or_b64 exec, exec, s[6:7]
	v_or_b32_e32 v66, 64, v128
	v_lshlrev_b32_e32 v64, 1, v66
	v_ashrrev_i32_e32 v65, 31, v64
	v_lshl_add_u64 v[64:65], v[64:65], 2, s[62:63]
	v_add_co_u32_e32 v64, vcc, 0xe000, v64
	s_movk_i32 s6, 0x1fcf
	s_nop 0
	v_addc_co_u32_e32 v65, vcc, 0, v65, vcc
	s_nop 1
	v_mov_b32_e32 v64, v245
	v_fmamk_f32 v64, v64, 0x3b800000, v174
	v_mul_f32_e32 v65, 0x4b800000, v64
	v_cmp_gt_f32_e32 vcc, s83, v64
	s_nop 1
	v_cndmask_b32_e32 v64, v64, v65, vcc
	v_rsq_f32_e32 v67, v64
	v_bitop3_b32 v64, v128, s6, 64 bitop3:0xc8
	v_lshlrev_b32_e32 v168, 1, v64
	v_lshl_add_u64 v[64:65], s[16:17], 0, v[168:169]
	v_mul_f32_e32 v68, 0x45800000, v67
	v_cndmask_b32_e32 v68, v67, v68, vcc
	v_pk_mul_f32 v[62:63], v[62:63], v[68:69] op_sel_hi:[1,0]
	v_pk_mul_f32 v[70:71], v[60:61], v[68:69] op_sel_hi:[1,0]
	v_pk_mul_f32 v[58:59], v[58:59], v[68:69] op_sel_hi:[1,0]
	v_pk_mul_f32 v[60:61], v[56:57], v[68:69] op_sel_hi:[1,0]
	s_and_saveexec_b64 s[6:7], s[2:3]
	s_xor_b64 s[6:7], exec, s[6:7]
	s_cbranch_execz .LBB0_428
	v_lshlrev_b64 v[56:57], 14, v[142:143]
	v_cvt_pk_bf16_f32 v67, v70, s0
	v_lshl_add_u64 v[56:57], v[64:65], 0, v[56:57]
	v_ashrrev_i32_e32 v141, 31, v140
	global_store_short v[56:57], v67, off
	v_lshlrev_b64 v[56:57], 14, v[140:141]
	v_cvt_pk_bf16_f32 v60, v60, s0
	v_lshl_add_u64 v[56:57], v[64:65], 0, v[56:57]
	v_ashrrev_i32_e32 v139, 31, v138
	global_store_short v[56:57], v60, off
	v_lshlrev_b64 v[56:57], 14, v[138:139]
	v_cvt_pk_bf16_f32 v60, v71, s0
	v_lshl_add_u64 v[56:57], v[64:65], 0, v[56:57]
	v_ashrrev_i32_e32 v137, 31, v136
	global_store_short v[56:57], v60, off
	v_lshlrev_b64 v[56:57], 14, v[136:137]
	v_cvt_pk_bf16_f32 v60, v61, s0
	v_lshl_add_u64 v[56:57], v[64:65], 0, v[56:57]
	v_ashrrev_i32_e32 v135, 31, v134
	global_store_short v[56:57], v60, off
	v_lshlrev_b64 v[56:57], 14, v[134:135]
	v_cvt_pk_bf16_f32 v60, v62, s0
	v_lshl_add_u64 v[56:57], v[64:65], 0, v[56:57]
	v_ashrrev_i32_e32 v133, 31, v132
	global_store_short v[56:57], v60, off
	v_lshlrev_b64 v[56:57], 14, v[132:133]
	v_cvt_pk_bf16_f32 v58, v58, s0
	v_lshl_add_u64 v[56:57], v[64:65], 0, v[56:57]
	v_ashrrev_i32_e32 v131, 31, v130
	global_store_short v[56:57], v58, off
	v_lshlrev_b64 v[56:57], 14, v[130:131]
	v_cvt_pk_bf16_f32 v58, v63, s0
	v_lshl_add_u64 v[56:57], v[64:65], 0, v[56:57]
	v_ashrrev_i32_e32 v121, 31, v120
	global_store_short v[56:57], v58, off
	v_lshlrev_b64 v[56:57], 14, v[120:121]
	v_cvt_pk_bf16_f32 v58, v59, s0
	v_lshl_add_u64 v[56:57], v[64:65], 0, v[56:57]
	global_store_short v[56:57], v58, off

.LBB0_434:
	s_or_b64 exec, exec, s[6:7]
	v_or_b32_e32 v50, 0x50, v128
	v_lshlrev_b32_e32 v48, 1, v50
	v_ashrrev_i32_e32 v49, 31, v48
	v_lshl_add_u64 v[48:49], v[48:49], 2, s[62:63]
	v_add_co_u32_e32 v48, vcc, 0xe000, v48
	s_movk_i32 s6, 0x1fdf
	s_nop 0
	v_addc_co_u32_e32 v49, vcc, 0, v49, vcc
	s_nop 1
	v_mov_b32_e32 v48, v246
	v_fmamk_f32 v48, v48, 0x3b800000, v174
	v_mul_f32_e32 v49, 0x4b800000, v48
	v_cmp_gt_f32_e32 vcc, s83, v48
	s_nop 1
	v_cndmask_b32_e32 v48, v48, v49, vcc
	v_rsq_f32_e32 v51, v48
	v_bitop3_b32 v48, v128, s6, v176 bitop3:0xc8
	v_lshlrev_b32_e32 v168, 1, v48
	v_lshl_add_u64 v[48:49], s[16:17], 0, v[168:169]
	v_mul_f32_e32 v52, 0x45800000, v51
	v_cndmask_b32_e32 v52, v51, v52, vcc
	v_pk_mul_f32 v[46:47], v[46:47], v[52:53] op_sel_hi:[1,0]
	v_pk_mul_f32 v[54:55], v[44:45], v[52:53] op_sel_hi:[1,0]
	v_pk_mul_f32 v[42:43], v[42:43], v[52:53] op_sel_hi:[1,0]
	v_pk_mul_f32 v[44:45], v[40:41], v[52:53] op_sel_hi:[1,0]
	s_and_saveexec_b64 s[6:7], s[2:3]
	s_xor_b64 s[6:7], exec, s[6:7]
	s_cbranch_execz .LBB0_436
	v_lshlrev_b64 v[40:41], 14, v[142:143]
	v_cvt_pk_bf16_f32 v51, v54, s0
	v_lshl_add_u64 v[40:41], v[48:49], 0, v[40:41]
	v_ashrrev_i32_e32 v141, 31, v140
	global_store_short v[40:41], v51, off
	v_lshlrev_b64 v[40:41], 14, v[140:141]
	v_cvt_pk_bf16_f32 v44, v44, s0
	v_lshl_add_u64 v[40:41], v[48:49], 0, v[40:41]
	v_ashrrev_i32_e32 v139, 31, v138
	global_store_short v[40:41], v44, off
	v_lshlrev_b64 v[40:41], 14, v[138:139]
	v_cvt_pk_bf16_f32 v44, v55, s0
	v_lshl_add_u64 v[40:41], v[48:49], 0, v[40:41]
	v_ashrrev_i32_e32 v137, 31, v136
	global_store_short v[40:41], v44, off
	v_lshlrev_b64 v[40:41], 14, v[136:137]
	v_cvt_pk_bf16_f32 v44, v45, s0
	v_lshl_add_u64 v[40:41], v[48:49], 0, v[40:41]
	v_ashrrev_i32_e32 v135, 31, v134
	global_store_short v[40:41], v44, off
	v_lshlrev_b64 v[40:41], 14, v[134:135]
	v_cvt_pk_bf16_f32 v44, v46, s0
	v_lshl_add_u64 v[40:41], v[48:49], 0, v[40:41]
	v_ashrrev_i32_e32 v133, 31, v132
	global_store_short v[40:41], v44, off
	v_lshlrev_b64 v[40:41], 14, v[132:133]
	v_cvt_pk_bf16_f32 v42, v42, s0
	v_lshl_add_u64 v[40:41], v[48:49], 0, v[40:41]
	v_ashrrev_i32_e32 v131, 31, v130
	global_store_short v[40:41], v42, off
	v_lshlrev_b64 v[40:41], 14, v[130:131]
	v_cvt_pk_bf16_f32 v42, v47, s0
	v_lshl_add_u64 v[40:41], v[48:49], 0, v[40:41]
	v_ashrrev_i32_e32 v121, 31, v120
	global_store_short v[40:41], v42, off
	v_lshlrev_b64 v[40:41], 14, v[120:121]
	v_cvt_pk_bf16_f32 v42, v43, s0
	v_lshl_add_u64 v[40:41], v[48:49], 0, v[40:41]
	global_store_short v[40:41], v42, off

.LBB0_442:
	s_or_b64 exec, exec, s[6:7]
	v_or_b32_e32 v34, 0x60, v128
	v_lshlrev_b32_e32 v32, 1, v34
	v_ashrrev_i32_e32 v33, 31, v32
	v_lshl_add_u64 v[32:33], v[32:33], 2, s[62:63]
	v_add_co_u32_e32 v32, vcc, 0xe000, v32
	s_movk_i32 s6, 0x1fef
	s_nop 0
	v_addc_co_u32_e32 v33, vcc, 0, v33, vcc
	s_nop 1
	v_mov_b32_e32 v32, v247
	v_fmamk_f32 v32, v32, 0x3b800000, v174
	v_mul_f32_e32 v33, 0x4b800000, v32
	v_cmp_gt_f32_e32 vcc, s83, v32
	s_nop 1
	v_cndmask_b32_e32 v32, v32, v33, vcc
	v_rsq_f32_e32 v35, v32
	v_bitop3_b32 v32, v128, s6, v177 bitop3:0xc8
	v_lshlrev_b32_e32 v168, 1, v32
	v_lshl_add_u64 v[32:33], s[16:17], 0, v[168:169]
	v_mul_f32_e32 v36, 0x45800000, v35
	v_cndmask_b32_e32 v36, v35, v36, vcc
	v_pk_mul_f32 v[30:31], v[30:31], v[36:37] op_sel_hi:[1,0]
	v_pk_mul_f32 v[38:39], v[28:29], v[36:37] op_sel_hi:[1,0]
	v_pk_mul_f32 v[26:27], v[26:27], v[36:37] op_sel_hi:[1,0]
	v_pk_mul_f32 v[28:29], v[24:25], v[36:37] op_sel_hi:[1,0]
	s_and_saveexec_b64 s[6:7], s[2:3]
	s_xor_b64 s[6:7], exec, s[6:7]
	s_cbranch_execz .LBB0_444
	v_lshlrev_b64 v[24:25], 14, v[142:143]
	v_cvt_pk_bf16_f32 v35, v38, s0
	v_lshl_add_u64 v[24:25], v[32:33], 0, v[24:25]
	v_ashrrev_i32_e32 v141, 31, v140
	global_store_short v[24:25], v35, off
	v_lshlrev_b64 v[24:25], 14, v[140:141]
	v_cvt_pk_bf16_f32 v28, v28, s0
	v_lshl_add_u64 v[24:25], v[32:33], 0, v[24:25]
	v_ashrrev_i32_e32 v139, 31, v138
	global_store_short v[24:25], v28, off
	v_lshlrev_b64 v[24:25], 14, v[138:139]
	v_cvt_pk_bf16_f32 v28, v39, s0
	v_lshl_add_u64 v[24:25], v[32:33], 0, v[24:25]
	v_ashrrev_i32_e32 v137, 31, v136
	global_store_short v[24:25], v28, off
	v_lshlrev_b64 v[24:25], 14, v[136:137]
	v_cvt_pk_bf16_f32 v28, v29, s0
	v_lshl_add_u64 v[24:25], v[32:33], 0, v[24:25]
	v_ashrrev_i32_e32 v135, 31, v134
	global_store_short v[24:25], v28, off
	v_lshlrev_b64 v[24:25], 14, v[134:135]
	v_cvt_pk_bf16_f32 v28, v30, s0
	v_lshl_add_u64 v[24:25], v[32:33], 0, v[24:25]
	v_ashrrev_i32_e32 v133, 31, v132
	global_store_short v[24:25], v28, off
	v_lshlrev_b64 v[24:25], 14, v[132:133]
	v_cvt_pk_bf16_f32 v26, v26, s0
	v_lshl_add_u64 v[24:25], v[32:33], 0, v[24:25]
	v_ashrrev_i32_e32 v131, 31, v130
	global_store_short v[24:25], v26, off
	v_lshlrev_b64 v[24:25], 14, v[130:131]
	v_cvt_pk_bf16_f32 v26, v31, s0
	v_lshl_add_u64 v[24:25], v[32:33], 0, v[24:25]
	v_ashrrev_i32_e32 v121, 31, v120
	global_store_short v[24:25], v26, off
	v_lshlrev_b64 v[24:25], 14, v[120:121]
	v_cvt_pk_bf16_f32 v26, v27, s0
	v_lshl_add_u64 v[24:25], v[32:33], 0, v[24:25]
	global_store_short v[24:25], v26, off

.LBB0_450:
	s_or_b64 exec, exec, s[6:7]
	v_or_b32_e32 v18, 0x70, v128
	v_lshlrev_b32_e32 v16, 1, v18
	v_ashrrev_i32_e32 v17, 31, v16
	v_lshl_add_u64 v[16:17], v[16:17], 2, s[62:63]
	v_add_co_u32_e32 v16, vcc, 0xe000, v16
	s_movk_i32 s6, 0x1fff
	s_nop 0
	v_addc_co_u32_e32 v17, vcc, 0, v17, vcc
	s_nop 1
	v_mov_b32_e32 v16, v248
	v_fmamk_f32 v16, v16, 0x3b800000, v174
	v_mul_f32_e32 v17, 0x4b800000, v16
	v_cmp_gt_f32_e32 vcc, s83, v16
	s_nop 1
	v_cndmask_b32_e32 v16, v16, v17, vcc
	v_rsq_f32_e32 v19, v16
	v_bitop3_b32 v16, v128, s6, v178 bitop3:0xc8
	v_lshlrev_b32_e32 v168, 1, v16
	v_lshl_add_u64 v[16:17], s[16:17], 0, v[168:169]
	v_mul_f32_e32 v20, 0x45800000, v19
	v_cndmask_b32_e32 v20, v19, v20, vcc
	v_pk_mul_f32 v[14:15], v[14:15], v[20:21] op_sel_hi:[1,0]
	v_pk_mul_f32 v[22:23], v[12:13], v[20:21] op_sel_hi:[1,0]
	v_pk_mul_f32 v[10:11], v[10:11], v[20:21] op_sel_hi:[1,0]
	v_pk_mul_f32 v[12:13], v[8:9], v[20:21] op_sel_hi:[1,0]
	s_and_saveexec_b64 s[6:7], s[2:3]
	s_xor_b64 s[6:7], exec, s[6:7]
	s_cbranch_execz .LBB0_452
	v_lshlrev_b64 v[8:9], 14, v[142:143]
	v_cvt_pk_bf16_f32 v19, v22, s0
	v_lshl_add_u64 v[8:9], v[16:17], 0, v[8:9]
	v_ashrrev_i32_e32 v141, 31, v140
	global_store_short v[8:9], v19, off
	v_lshlrev_b64 v[8:9], 14, v[140:141]
	v_cvt_pk_bf16_f32 v12, v12, s0
	v_lshl_add_u64 v[8:9], v[16:17], 0, v[8:9]
	v_ashrrev_i32_e32 v139, 31, v138
	global_store_short v[8:9], v12, off
	v_lshlrev_b64 v[8:9], 14, v[138:139]
	v_cvt_pk_bf16_f32 v12, v23, s0
	v_lshl_add_u64 v[8:9], v[16:17], 0, v[8:9]
	v_ashrrev_i32_e32 v137, 31, v136
	global_store_short v[8:9], v12, off
	v_lshlrev_b64 v[8:9], 14, v[136:137]
	v_cvt_pk_bf16_f32 v12, v13, s0
	v_lshl_add_u64 v[8:9], v[16:17], 0, v[8:9]
	v_ashrrev_i32_e32 v135, 31, v134
	global_store_short v[8:9], v12, off
	v_lshlrev_b64 v[8:9], 14, v[134:135]
	v_cvt_pk_bf16_f32 v12, v14, s0
	v_lshl_add_u64 v[8:9], v[16:17], 0, v[8:9]
	v_ashrrev_i32_e32 v133, 31, v132
	global_store_short v[8:9], v12, off
	v_lshlrev_b64 v[8:9], 14, v[132:133]
	v_cvt_pk_bf16_f32 v10, v10, s0
	v_lshl_add_u64 v[8:9], v[16:17], 0, v[8:9]
	v_ashrrev_i32_e32 v131, 31, v130
	global_store_short v[8:9], v10, off
	v_lshlrev_b64 v[8:9], 14, v[130:131]
	v_cvt_pk_bf16_f32 v10, v15, s0
	v_lshl_add_u64 v[8:9], v[16:17], 0, v[8:9]
	v_ashrrev_i32_e32 v121, 31, v120
	global_store_short v[8:9], v10, off
	v_lshlrev_b64 v[8:9], 14, v[120:121]
	v_cvt_pk_bf16_f32 v10, v11, s0
	v_lshl_add_u64 v[8:9], v[16:17], 0, v[8:9]
	global_store_short v[8:9], v10, off

.LBB0_468:
	v_or_b32_e32 v168, v186, v171
	v_lshlrev_b32_e32 v88, 1, v168
	v_mov_b32_e32 v89, v169
	v_lshl_add_u64 v[88:89], v[88:89], 2, s[22:23]
	v_mov_b64_e32 v[250:251], v[88:89]
	global_load_dword v88, v[88:89], off
	v_lshl_add_u64 v[92:93], v[168:169], 2, s[24:25]
	global_load_dword v242, v[250:251], off offset:128
	global_load_dword v243, v[250:251], off offset:256
	global_load_dword v244, v[250:251], off offset:384
	global_load_dword v245, v[92:93], off offset:64
	global_load_dword v246, v[92:93], off offset:128
	global_load_dword v247, v[92:93], off offset:192
	s_waitcnt vmcnt(11)
	v_lshrrev_b32_e32 v109, 4, v187
	v_lshlrev_b32_e32 v104, 2, v109
	s_mov_b32 s90, s96
	v_cmp_lt_i32_e64 s[6:7], 5, v185
	v_cvt_f32_ubyte0_e32 v107, v104
	v_or_b32_e32 v108, 1, v104
	v_or_b32_e32 v105, 2, v104
	v_or_b32_e32 v106, 3, v104
	s_waitcnt vmcnt(0)
	v_fmamk_f32 v88, v88, 0x3aaaaaab, v174
	v_cmp_gt_f32_e32 vcc, s83, v88
	v_mul_f32_e32 v89, 0x4b800000, v88
	s_nop 0
	v_cndmask_b32_e32 v88, v88, v89, vcc
	v_rsq_f32_e32 v88, v88
	s_nop 0
	v_mul_f32_e32 v89, 0x45800000, v88
	v_cndmask_b32_e32 v94, v88, v89, vcc
	global_load_dword v88, v[92:93], off
	v_pk_mul_f32 v[90:91], v[166:167], v[94:95] op_sel_hi:[1,0]
	v_pk_mul_f32 v[100:101], v[162:163], v[94:95] op_sel_hi:[1,0]
	v_pk_mul_f32 v[102:103], v[160:161], v[94:95] op_sel_hi:[1,0]
	s_waitcnt vmcnt(0)
	v_cvt_f32_i32_e32 v110, v88
	v_pk_mul_f32 v[88:89], v[164:165], v[94:95] op_sel_hi:[1,0]
	s_and_saveexec_b64 s[2:3], s[6:7]
	s_cbranch_execz .LBB0_470
	v_mul_f32_e32 v95, 0xbf549a78, v107
	v_cmp_gt_f32_e32 vcc, s91, v95
	v_cvt_f32_ubyte0_e32 v97, v108
	v_mul_f32_e32 v98, 0xbf549a78, v97
	v_cndmask_b32_e32 v96, 0, v180, vcc
	v_fmac_f32_e32 v96, 0xbf549a78, v107
	v_exp_f32_e32 v96, v96
	v_cndmask_b32_e32 v95, 0, v179, vcc
	v_cmp_gt_f32_e32 vcc, s91, v98
	v_cvt_f32_ubyte0_e32 v114, v106
	v_ldexp_f32 v95, v96, v95
	v_mul_f32_e32 v95, v95, v110
	v_mul_f32_e32 v96, 0.15915494, v95
	v_rndne_f32_e32 v96, v96
	v_fma_f32 v99, v95, 0.15915494, -v96
	v_fmac_f32_e32 v99, 0x31dc9c88, v95
	v_cndmask_b32_e32 v95, 0, v180, vcc
	v_fmac_f32_e32 v95, 0xbf549a78, v97
	v_exp_f32_e32 v95, v95
	v_cndmask_b32_e32 v97, 0, v179, vcc
	v_sin_f32_e32 v96, v99
	v_cos_f32_e32 v98, v99
	v_ldexp_f32 v95, v95, v97
	v_mul_f32_e32 v95, v95, v110
	v_mul_f32_e32 v97, 0.15915494, v95
	v_rndne_f32_e32 v97, v97
	v_fma_f32 v99, v95, 0.15915494, -v97
	v_fmac_f32_e32 v99, 0x31dc9c88, v95
	v_cvt_f32_ubyte0_e32 v95, v105
	v_mul_f32_e32 v111, 0xbf549a78, v95
	v_cmp_gt_f32_e32 vcc, s91, v111
	v_mul_f32_e32 v115, 0xbf549a78, v114
	v_sin_f32_e32 v97, v99
	v_cndmask_b32_e32 v111, 0, v180, vcc
	v_fmac_f32_e32 v111, 0xbf549a78, v95
	v_exp_f32_e32 v95, v111
	v_cndmask_b32_e32 v111, 0, v179, vcc
	v_cmp_gt_f32_e32 vcc, s91, v115
	v_cos_f32_e32 v99, v99
	v_ldexp_f32 v95, v95, v111
	v_cndmask_b32_e32 v115, 0, v180, vcc
	v_fmac_f32_e32 v115, 0xbf549a78, v114
	v_exp_f32_e32 v115, v115
	v_cndmask_b32_e32 v117, 0, v179, vcc
	v_mul_f32_e32 v95, v95, v110
	v_mul_f32_e32 v111, 0.15915494, v95
	v_ldexp_f32 v115, v115, v117
	v_mul_f32_e32 v115, v115, v110
	v_rndne_f32_e32 v111, v111
	v_mul_f32_e32 v117, 0.15915494, v115
	v_fma_f32 v111, v95, 0.15915494, -v111
	v_rndne_f32_e32 v117, v117
	v_fmac_f32_e32 v111, 0x31dc9c88, v95
	v_fma_f32 v117, v115, 0.15915494, -v117
	v_sin_f32_e32 v95, v111
	v_cos_f32_e32 v111, v111
	v_fmac_f32_e32 v117, 0x31dc9c88, v115
	v_sin_f32_e32 v119, v117
	v_cos_f32_e32 v118, v117
	v_mul_f32_e32 v116, v95, v100
	v_mul_f32_e32 v120, v111, v100
	v_mov_b32_e32 v100, v91
	v_mul_f32_e32 v114, v111, v90
	v_mul_f32_e32 v122, v95, v90
	v_pk_mul_f32 v[90:91], v[118:119], v[100:101]
	v_pk_mul_f32 v[112:113], v[96:97], v[102:103]
	v_mov_b32_e32 v115, v90
	v_mov_b32_e32 v117, v91
	v_mov_b32_e32 v90, v119
	v_mov_b32_e32 v91, v118
	v_pk_mul_f32 v[90:91], v[90:91], v[100:101]
	v_pk_mul_f32 v[102:103], v[98:99], v[102:103]
	v_mov_b32_e32 v123, v90
	v_mov_b32_e32 v121, v91
	v_pk_fma_f32 v[98:99], v[98:99], v[88:89], v[112:113] neg_lo:[0,0,1] neg_hi:[0,0,1]
	v_pk_add_f32 v[90:91], v[114:115], v[116:117] neg_lo:[0,1] neg_hi:[0,1]
	v_pk_fma_f32 v[102:103], v[96:97], v[88:89], v[102:103]
	v_pk_add_f32 v[100:101], v[122:123], v[120:121]
	v_mov_b32_e32 v88, v98
	v_mov_b32_e32 v89, v99

.LBB0_492:
	s_nop 0
	v_or_b32_e32 v72, 16, v168
	v_lshlrev_b32_e32 v74, 1, v72
	v_mov_b32_e32 v75, v169
	v_lshl_add_u64 v[74:75], v[74:75], 2, s[22:23]
	v_mov_b32_e32 v73, v242
	s_nop 0
	v_mov_b32_e32 v74, v245
	v_fmamk_f32 v73, v73, 0x3aaaaaab, v174
	v_mul_f32_e32 v75, 0x4b800000, v73
	v_cmp_gt_f32_e32 vcc, s83, v73
	s_nop 0
	v_cvt_f32_i32_e32 v77, v74
	v_cndmask_b32_e32 v73, v73, v75, vcc
	v_rsq_f32_e32 v73, v73
	s_nop 0
	v_mul_f32_e32 v74, 0x45800000, v73
	v_cndmask_b32_e32 v74, v73, v74, vcc
	v_pk_mul_f32 v[82:83], v[70:71], v[74:75] op_sel_hi:[1,0]
	v_pk_mul_f32 v[78:79], v[68:69], v[74:75] op_sel_hi:[1,0]
	v_pk_mul_f32 v[80:81], v[66:67], v[74:75] op_sel_hi:[1,0]
	v_pk_mul_f32 v[66:67], v[64:65], v[74:75] op_sel_hi:[1,0]
	s_and_saveexec_b64 s[66:67], s[6:7]
	s_cbranch_execz .LBB0_494
	v_mul_f32_e32 v64, 0xbf549a78, v107
	v_cmp_gt_f32_e32 vcc, s91, v64
	v_cvt_f32_ubyte0_e32 v68, v108
	v_mul_f32_e32 v69, 0xbf549a78, v68
	v_cndmask_b32_e32 v65, 0, v180, vcc
	v_fmac_f32_e32 v65, 0xbf549a78, v107
	v_exp_f32_e32 v65, v65
	v_cndmask_b32_e32 v64, 0, v179, vcc
	v_cmp_gt_f32_e32 vcc, s91, v69
	v_cvt_f32_ubyte0_e32 v70, v105
	v_ldexp_f32 v64, v65, v64
	v_mul_f32_e32 v64, v64, v77
	v_mul_f32_e32 v65, 0.15915494, v64
	v_rndne_f32_e32 v65, v65
	v_fma_f32 v65, v64, 0.15915494, -v65
	v_fmac_f32_e32 v65, 0x31dc9c88, v64
	v_cndmask_b32_e32 v64, 0, v180, vcc
	v_fmac_f32_e32 v64, 0xbf549a78, v68
	v_mul_f32_e32 v71, 0xbf549a78, v70
	v_cvt_f32_ubyte0_e32 v85, v106
	v_exp_f32_e32 v69, v64
	v_sin_f32_e32 v64, v65
	v_cos_f32_e32 v68, v65
	v_cndmask_b32_e32 v65, 0, v179, vcc
	v_cmp_gt_f32_e32 vcc, s91, v71
	v_mul_f32_e32 v86, 0xbf549a78, v85
	v_ldexp_f32 v65, v69, v65
	v_cndmask_b32_e32 v71, 0, v180, vcc
	v_cndmask_b32_e32 v75, 0, v179, vcc
	v_cmp_gt_f32_e32 vcc, s91, v86
	v_fmac_f32_e32 v71, 0xbf549a78, v70
	v_exp_f32_e32 v73, v71
	v_cndmask_b32_e32 v86, 0, v180, vcc
	v_fmac_f32_e32 v86, 0xbf549a78, v85
	v_exp_f32_e32 v85, v86
	v_ldexp_f32 v73, v73, v75
	v_cndmask_b32_e32 v87, 0, v179, vcc
	v_mul_f32_e32 v73, v73, v77
	v_ldexp_f32 v85, v85, v87
	v_mul_f32_e32 v75, 0.15915494, v73
	v_mul_f32_e32 v85, v85, v77
	v_rndne_f32_e32 v75, v75
	v_mul_f32_e32 v87, 0.15915494, v85
	v_mul_f32_e32 v65, v65, v77
	v_fma_f32 v75, v73, 0.15915494, -v75
	v_rndne_f32_e32 v87, v87
	v_mul_f32_e32 v69, 0.15915494, v65
	v_fmac_f32_e32 v75, 0x31dc9c88, v73
	v_fma_f32 v87, v85, 0.15915494, -v87
	v_rndne_f32_e32 v69, v69
	v_sin_f32_e32 v73, v75
	v_cos_f32_e32 v75, v75
	v_fmac_f32_e32 v87, 0x31dc9c88, v85
	v_fma_f32 v69, v65, 0.15915494, -v69
	v_sin_f32_e32 v91, v87
	v_cos_f32_e32 v90, v87
	v_fmac_f32_e32 v69, 0x31dc9c88, v65
	v_sin_f32_e32 v65, v69
	v_cos_f32_e32 v69, v69
	v_mul_f32_e32 v88, v73, v80
	v_mul_f32_e32 v94, v75, v80
	v_mov_b32_e32 v80, v83
	v_mul_f32_e32 v86, v75, v82
	v_mul_f32_e32 v96, v73, v82
	v_pk_mul_f32 v[82:83], v[90:91], v[80:81]
	v_pk_mul_f32 v[70:71], v[64:65], v[66:67]
	v_mov_b32_e32 v87, v82
	v_mov_b32_e32 v89, v83
	v_mov_b32_e32 v82, v91
	v_mov_b32_e32 v83, v90
	v_pk_mul_f32 v[80:81], v[82:83], v[80:81]
	v_pk_mul_f32 v[66:67], v[68:69], v[66:67]
	v_mov_b32_e32 v97, v80
	v_mov_b32_e32 v95, v81
	v_pk_fma_f32 v[68:69], v[68:69], v[78:79], v[70:71] neg_lo:[0,0,1] neg_hi:[0,0,1]
	v_pk_add_f32 v[82:83], v[86:87], v[88:89] neg_lo:[0,1] neg_hi:[0,1]
	v_pk_fma_f32 v[66:67], v[64:65], v[78:79], v[66:67]
	v_pk_add_f32 v[80:81], v[96:97], v[94:95]
	v_mov_b32_e32 v78, v68
	v_mov_b32_e32 v79, v69

.LBB0_516:
	s_nop 0
	v_or_b32_e32 v49, 32, v168
	v_lshlrev_b32_e32 v50, 1, v49
	v_mov_b32_e32 v51, v169
	v_lshl_add_u64 v[50:51], v[50:51], 2, s[22:23]
	v_mov_b32_e32 v48, v243
	s_nop 0
	v_mov_b32_e32 v50, v246
	v_fmamk_f32 v48, v48, 0x3aaaaaab, v174
	v_mul_f32_e32 v51, 0x4b800000, v48
	v_cmp_gt_f32_e32 vcc, s83, v48
	s_nop 0
	v_cvt_f32_i32_e32 v56, v50
	v_cndmask_b32_e32 v48, v48, v51, vcc
	v_rsq_f32_e32 v48, v48
	s_nop 0
	v_mul_f32_e32 v50, 0x45800000, v48
	v_cndmask_b32_e32 v48, v48, v50, vcc
	v_pk_mul_f32 v[54:55], v[46:47], v[48:49] op_sel_hi:[1,0]
	v_pk_mul_f32 v[50:51], v[44:45], v[48:49] op_sel_hi:[1,0]
	v_pk_mul_f32 v[52:53], v[42:43], v[48:49] op_sel_hi:[1,0]
	v_pk_mul_f32 v[42:43], v[40:41], v[48:49] op_sel_hi:[1,0]
	s_and_saveexec_b64 s[66:67], s[6:7]
	s_cbranch_execz .LBB0_518
	v_mul_f32_e32 v40, 0xbf549a78, v107
	v_cmp_gt_f32_e32 vcc, s91, v40
	v_cvt_f32_ubyte0_e32 v44, v108
	v_mul_f32_e32 v45, 0xbf549a78, v44
	v_cndmask_b32_e32 v41, 0, v180, vcc
	v_fmac_f32_e32 v41, 0xbf549a78, v107
	v_exp_f32_e32 v41, v41
	v_cndmask_b32_e32 v40, 0, v179, vcc
	v_cmp_gt_f32_e32 vcc, s91, v45
	v_cvt_f32_ubyte0_e32 v46, v105
	v_ldexp_f32 v40, v41, v40
	v_mul_f32_e32 v40, v40, v56
	v_mul_f32_e32 v41, 0.15915494, v40
	v_rndne_f32_e32 v41, v41
	v_fma_f32 v41, v40, 0.15915494, -v41
	v_fmac_f32_e32 v41, 0x31dc9c88, v40
	v_cndmask_b32_e32 v40, 0, v180, vcc
	v_fmac_f32_e32 v40, 0xbf549a78, v44
	v_mul_f32_e32 v47, 0xbf549a78, v46
	v_exp_f32_e32 v45, v40
	v_sin_f32_e32 v40, v41
	v_cos_f32_e32 v44, v41
	v_cndmask_b32_e32 v41, 0, v179, vcc
	v_cmp_gt_f32_e32 vcc, s91, v47
	v_ldexp_f32 v41, v45, v41
	v_mul_f32_e32 v41, v41, v56
	v_cndmask_b32_e32 v47, 0, v180, vcc
	v_fmac_f32_e32 v47, 0xbf549a78, v46
	v_exp_f32_e32 v57, v47
	v_cndmask_b32_e32 v58, 0, v179, vcc
	v_mul_f32_e32 v45, 0.15915494, v41
	v_rndne_f32_e32 v45, v45
	v_ldexp_f32 v57, v57, v58
	v_mul_f32_e32 v57, v57, v56
	v_mul_f32_e32 v58, 0.15915494, v57
	v_rndne_f32_e32 v58, v58
	v_fma_f32 v58, v57, 0.15915494, -v58
	v_fmac_f32_e32 v58, 0x31dc9c88, v57
	v_sin_f32_e32 v57, v58
	v_cos_f32_e32 v59, v58
	v_cvt_f32_ubyte0_e32 v58, v106
	v_mul_f32_e32 v60, 0xbf549a78, v58
	v_cmp_gt_f32_e32 vcc, s91, v60
	v_fma_f32 v45, v41, 0.15915494, -v45
	v_fmac_f32_e32 v45, 0x31dc9c88, v41
	v_cndmask_b32_e32 v60, 0, v180, vcc
	v_fmac_f32_e32 v60, 0xbf549a78, v58
	v_exp_f32_e32 v61, v60
	v_cndmask_b32_e32 v62, 0, v179, vcc
	v_sin_f32_e32 v41, v45
	v_cos_f32_e32 v45, v45
	v_ldexp_f32 v61, v61, v62
	v_mul_f32_e32 v61, v61, v56
	v_mul_f32_e32 v62, 0.15915494, v61
	v_rndne_f32_e32 v62, v62
	v_fma_f32 v62, v61, 0.15915494, -v62
	v_fmac_f32_e32 v62, 0x31dc9c88, v61
	v_sin_f32_e32 v63, v62
	v_cos_f32_e32 v62, v62
	v_mul_f32_e32 v60, v57, v52
	v_mul_f32_e32 v64, v59, v52
	v_mov_b32_e32 v52, v55
	v_mul_f32_e32 v58, v59, v54
	v_mul_f32_e32 v66, v57, v54
	v_pk_mul_f32 v[54:55], v[62:63], v[52:53]
	v_pk_mul_f32 v[46:47], v[40:41], v[42:43]
	v_mov_b32_e32 v59, v54
	v_mov_b32_e32 v61, v55
	v_mov_b32_e32 v54, v63
	v_mov_b32_e32 v55, v62
	v_pk_mul_f32 v[52:53], v[54:55], v[52:53]
	v_pk_mul_f32 v[42:43], v[44:45], v[42:43]
	v_mov_b32_e32 v67, v52
	v_mov_b32_e32 v65, v53
	v_pk_fma_f32 v[44:45], v[44:45], v[50:51], v[46:47] neg_lo:[0,0,1] neg_hi:[0,0,1]
	v_pk_add_f32 v[54:55], v[58:59], v[60:61] neg_lo:[0,1] neg_hi:[0,1]
	v_pk_fma_f32 v[42:43], v[40:41], v[50:51], v[42:43]
	v_pk_add_f32 v[52:53], v[66:67], v[64:65]
	v_mov_b32_e32 v50, v44
	v_mov_b32_e32 v51, v45

.LBB0_540:
	s_nop 0
	v_or_b32_e32 v25, 48, v168
	v_lshlrev_b32_e32 v168, 1, v25
	v_lshl_add_u64 v[26:27], v[168:169], 2, s[22:23]
	v_mov_b32_e32 v24, v244
	s_nop 0
	v_mov_b32_e32 v26, v247
	v_fmamk_f32 v24, v24, 0x3aaaaaab, v174
	v_mul_f32_e32 v27, 0x4b800000, v24
	v_cmp_gt_f32_e32 vcc, s83, v24
	s_nop 0
	v_cvt_f32_i32_e32 v32, v26
	v_cndmask_b32_e32 v24, v24, v27, vcc
	v_rsq_f32_e32 v24, v24
	s_nop 0
	v_mul_f32_e32 v26, 0x45800000, v24
	v_cndmask_b32_e32 v24, v24, v26, vcc
	v_pk_mul_f32 v[30:31], v[22:23], v[24:25] op_sel_hi:[1,0]
	v_pk_mul_f32 v[26:27], v[20:21], v[24:25] op_sel_hi:[1,0]
	v_pk_mul_f32 v[28:29], v[18:19], v[24:25] op_sel_hi:[1,0]
	v_pk_mul_f32 v[18:19], v[16:17], v[24:25] op_sel_hi:[1,0]
	s_and_saveexec_b64 s[66:67], s[6:7]
	s_mov_b32 s96, s90
	s_cbranch_execz .LBB0_542
	v_mul_f32_e32 v16, 0xbf549a78, v107
	v_cmp_gt_f32_e32 vcc, s91, v16
	v_cvt_f32_ubyte0_e32 v20, v108
	v_mul_f32_e32 v21, 0xbf549a78, v20
	v_cndmask_b32_e32 v17, 0, v180, vcc
	v_fmac_f32_e32 v17, 0xbf549a78, v107
	v_exp_f32_e32 v17, v17
	v_cndmask_b32_e32 v16, 0, v179, vcc
	v_cmp_gt_f32_e32 vcc, s91, v21
	v_cvt_f32_ubyte0_e32 v22, v105
	v_ldexp_f32 v16, v17, v16
	v_mul_f32_e32 v16, v16, v32
	v_mul_f32_e32 v17, 0.15915494, v16
	v_rndne_f32_e32 v17, v17
	v_fma_f32 v17, v16, 0.15915494, -v17
	v_fmac_f32_e32 v17, 0x31dc9c88, v16
	v_cndmask_b32_e32 v16, 0, v180, vcc
	v_fmac_f32_e32 v16, 0xbf549a78, v20
	v_mul_f32_e32 v23, 0xbf549a78, v22
	v_exp_f32_e32 v21, v16
	v_sin_f32_e32 v16, v17
	v_cos_f32_e32 v20, v17
	v_cndmask_b32_e32 v17, 0, v179, vcc
	v_cmp_gt_f32_e32 vcc, s91, v23
	v_ldexp_f32 v17, v21, v17
	v_mul_f32_e32 v17, v17, v32
	v_cndmask_b32_e32 v23, 0, v180, vcc
	v_fmac_f32_e32 v23, 0xbf549a78, v22
	v_exp_f32_e32 v33, v23
	v_cndmask_b32_e32 v34, 0, v179, vcc
	v_mul_f32_e32 v21, 0.15915494, v17
	v_rndne_f32_e32 v21, v21
	v_ldexp_f32 v33, v33, v34
	v_mul_f32_e32 v33, v33, v32
	v_mul_f32_e32 v34, 0.15915494, v33
	v_rndne_f32_e32 v34, v34
	v_fma_f32 v34, v33, 0.15915494, -v34
	v_fmac_f32_e32 v34, 0x31dc9c88, v33
	v_sin_f32_e32 v33, v34
	v_cos_f32_e32 v35, v34
	v_cvt_f32_ubyte0_e32 v34, v106
	v_mul_f32_e32 v36, 0xbf549a78, v34
	v_cmp_gt_f32_e32 vcc, s91, v36
	v_fma_f32 v21, v17, 0.15915494, -v21
	v_fmac_f32_e32 v21, 0x31dc9c88, v17
	v_cndmask_b32_e32 v36, 0, v180, vcc
	v_fmac_f32_e32 v36, 0xbf549a78, v34
	v_exp_f32_e32 v37, v36
	v_cndmask_b32_e32 v38, 0, v179, vcc
	v_sin_f32_e32 v17, v21
	v_cos_f32_e32 v21, v21
	v_ldexp_f32 v37, v37, v38
	v_mul_f32_e32 v37, v37, v32
	v_mul_f32_e32 v38, 0.15915494, v37
	v_rndne_f32_e32 v38, v38
	v_fma_f32 v38, v37, 0.15915494, -v38
	v_fmac_f32_e32 v38, 0x31dc9c88, v37
	v_sin_f32_e32 v39, v38
	v_cos_f32_e32 v38, v38
	v_mul_f32_e32 v36, v33, v28
	v_mul_f32_e32 v40, v35, v28
	v_mov_b32_e32 v28, v31
	v_mul_f32_e32 v34, v35, v30
	v_mul_f32_e32 v42, v33, v30
	v_pk_mul_f32 v[30:31], v[38:39], v[28:29]
	v_pk_mul_f32 v[22:23], v[16:17], v[18:19]
	v_mov_b32_e32 v35, v30
	v_mov_b32_e32 v37, v31
	v_mov_b32_e32 v30, v39
	v_mov_b32_e32 v31, v38
	v_pk_mul_f32 v[28:29], v[30:31], v[28:29]
	v_pk_mul_f32 v[18:19], v[20:21], v[18:19]
	v_mov_b32_e32 v43, v28
	v_mov_b32_e32 v41, v29
	v_pk_fma_f32 v[20:21], v[20:21], v[26:27], v[22:23] neg_lo:[0,0,1] neg_hi:[0,0,1]
	v_pk_add_f32 v[30:31], v[34:35], v[36:37] neg_lo:[0,1] neg_hi:[0,1]
	v_pk_fma_f32 v[18:19], v[16:17], v[26:27], v[18:19]
	v_pk_add_f32 v[28:29], v[42:43], v[40:41]
	v_mov_b32_e32 v26, v20
	v_mov_b32_e32 v27, v21

.LBB0_1160:
	v_mov_b32_e32 v129, v198
	s_movk_i32 s6, 0x1f8f
	v_ashrrev_i32_e32 v128, 1, v129
	v_and_b32_e32 v128, 0xffffff80, v128
	v_and_b32_e32 v132, 15, v129
	v_lshl_add_u32 v133, v149, 8, v128
	v_or_b32_e32 v128, v133, v132
	v_lshlrev_b32_e32 v130, 1, v128
	v_ashrrev_i32_e32 v131, 31, v130
	v_lshl_add_u64 v[130:131], v[130:131], 2, s[62:63]
	v_add_co_u32_e32 v130, vcc, s78, v130
	s_nop 1
	v_addc_co_u32_e32 v131, vcc, 0, v131, vcc
	global_load_dword v134, v[130:131], off offset:4
	global_load_dword v242, v[130:131], off offset:132
	global_load_dword v243, v[130:131], off offset:260
	global_load_dword v244, v[130:131], off offset:388
	global_load_dword v245, v[130:131], off offset:516
	global_load_dword v246, v[130:131], off offset:644
	global_load_dword v247, v[130:131], off offset:772
	global_load_dword v248, v[130:131], off offset:900
	v_lshlrev_b32_e32 v130, 8, v148
	v_and_or_b32 v168, v129, s61, v130
	v_lshrrev_b32_e32 v130, 1, v129
	v_and_b32_e32 v129, 64, v129
	v_lshrrev_b32_e32 v135, 7, v168
	v_and_b32_e32 v162, 24, v130
	v_cmp_ne_u32_e64 s[2:3], 0, v129
	v_ashrrev_i32_e32 v129, 10, v133
	v_bitop3_b32 v130, v133, s6, v132 bitop3:0xc8
	s_mov_b32 s6, 0x3fffff8
	v_and_or_b32 v129, v129, s6, v135
	v_mov_b32_e32 v131, v169
	v_lshlrev_b32_e32 v130, 1, v130
	v_lshlrev_b32_e32 v163, 6, v129
	v_lshl_add_u64 v[150:151], s[16:17], 0, v[130:131]
	v_or_b32_e32 v142, v163, v162
	v_ashrrev_i32_e32 v143, 31, v142
	v_or_b32_e32 v140, 4, v142
	v_or_b32_e32 v138, 1, v142
	v_or_b32_e32 v136, 5, v142
	v_or_b32_e32 v132, 6, v142
	s_waitcnt vmcnt(0)
	v_fmamk_f32 v129, v134, 0x3b800000, v174
	v_mul_f32_e32 v130, 0x4b800000, v129
	v_cmp_gt_f32_e32 vcc, s79, v129
	v_or_b32_e32 v134, 2, v142
	s_nop 0
	v_cndmask_b32_e32 v129, v129, v130, vcc
	v_rsq_f32_e32 v129, v129
	v_or_b32_e32 v130, 3, v142
	v_mul_f32_e32 v131, 0x45800000, v129
	v_cndmask_b32_e32 v144, v129, v131, vcc
	v_pk_mul_f32 v[126:127], v[126:127], v[144:145] op_sel_hi:[1,0]
	v_pk_mul_f32 v[152:153], v[124:125], v[144:145] op_sel_hi:[1,0]
	v_pk_mul_f32 v[124:125], v[122:123], v[144:145] op_sel_hi:[1,0]
	v_pk_mul_f32 v[146:147], v[120:121], v[144:145] op_sel_hi:[1,0]
	v_or_b32_e32 v120, 7, v142
	s_and_saveexec_b64 s[6:7], s[2:3]
	s_xor_b64 s[6:7], exec, s[6:7]
	s_cbranch_execz .LBB0_1162
	v_lshlrev_b64 v[122:123], 14, v[142:143]
	v_cvt_pk_bf16_f32 v121, v152, s0
	v_lshl_add_u64 v[122:123], v[150:151], 0, v[122:123]
	v_ashrrev_i32_e32 v141, 31, v140
	global_store_short v[122:123], v121, off
	v_lshlrev_b64 v[122:123], 14, v[140:141]
	v_cvt_pk_bf16_f32 v121, v146, s0
	v_lshl_add_u64 v[122:123], v[150:151], 0, v[122:123]
	v_ashrrev_i32_e32 v139, 31, v138
	global_store_short v[122:123], v121, off
	v_lshlrev_b64 v[122:123], 14, v[138:139]
	v_cvt_pk_bf16_f32 v121, v153, s0
	v_lshl_add_u64 v[122:123], v[150:151], 0, v[122:123]
	v_ashrrev_i32_e32 v137, 31, v136
	global_store_short v[122:123], v121, off
	v_lshlrev_b64 v[122:123], 14, v[136:137]
	v_cvt_pk_bf16_f32 v121, v147, s0
	v_lshl_add_u64 v[122:123], v[150:151], 0, v[122:123]
	v_ashrrev_i32_e32 v135, 31, v134
	global_store_short v[122:123], v121, off
	v_lshlrev_b64 v[122:123], 14, v[134:135]
	v_cvt_pk_bf16_f32 v121, v126, s0
	v_lshl_add_u64 v[122:123], v[150:151], 0, v[122:123]
	v_ashrrev_i32_e32 v133, 31, v132
	global_store_short v[122:123], v121, off
	v_lshlrev_b64 v[122:123], 14, v[132:133]
	v_cvt_pk_bf16_f32 v121, v124, s0
	v_lshl_add_u64 v[122:123], v[150:151], 0, v[122:123]
	v_ashrrev_i32_e32 v131, 31, v130
	global_store_short v[122:123], v121, off
	v_lshlrev_b64 v[122:123], 14, v[130:131]
	v_cvt_pk_bf16_f32 v121, v127, s0
	v_lshl_add_u64 v[122:123], v[150:151], 0, v[122:123]
	global_store_short v[122:123], v121, off
	v_ashrrev_i32_e32 v121, 31, v120
	v_lshlrev_b64 v[122:123], 14, v[120:121]
	v_cvt_pk_bf16_f32 v124, v125, s0
	v_lshl_add_u64 v[122:123], v[150:151], 0, v[122:123]
	global_store_short v[122:123], v124, off

.LBB0_1168:
	s_or_b64 exec, exec, s[6:7]
	v_or_b32_e32 v152, 16, v128
	v_lshlrev_b32_e32 v150, 1, v152
	v_ashrrev_i32_e32 v151, 31, v150
	v_lshl_add_u64 v[150:151], v[150:151], 2, s[62:63]
	v_add_co_u32_e32 v150, vcc, 0xe000, v150
	s_movk_i32 s6, 0x1f9f
	s_nop 0
	v_addc_co_u32_e32 v151, vcc, 0, v151, vcc
	s_nop 1
	v_mov_b32_e32 v113, v242
	v_fmamk_f32 v113, v113, 0x3b800000, v174
	v_mul_f32_e32 v115, 0x4b800000, v113
	v_cmp_gt_f32_e32 vcc, s79, v113
	s_nop 1
	v_cndmask_b32_e32 v113, v113, v115, vcc
	v_rsq_f32_e32 v113, v113
	v_bitop3_b32 v115, v128, s6, 16 bitop3:0xc8
	v_lshlrev_b32_e32 v168, 1, v115
	v_lshl_add_u64 v[150:151], s[16:17], 0, v[168:169]
	v_mul_f32_e32 v115, 0x45800000, v113
	v_cndmask_b32_e32 v154, v113, v115, vcc
	v_pk_mul_f32 v[110:111], v[110:111], v[154:155] op_sel_hi:[1,0]
	v_pk_mul_f32 v[156:157], v[108:109], v[154:155] op_sel_hi:[1,0]
	v_pk_mul_f32 v[106:107], v[106:107], v[154:155] op_sel_hi:[1,0]
	v_pk_mul_f32 v[108:109], v[104:105], v[154:155] op_sel_hi:[1,0]
	s_and_saveexec_b64 s[6:7], s[2:3]
	s_xor_b64 s[6:7], exec, s[6:7]
	s_cbranch_execz .LBB0_1170
	v_lshlrev_b64 v[104:105], 14, v[142:143]
	v_cvt_pk_bf16_f32 v113, v156, s0
	v_lshl_add_u64 v[104:105], v[150:151], 0, v[104:105]
	v_ashrrev_i32_e32 v141, 31, v140
	global_store_short v[104:105], v113, off
	v_lshlrev_b64 v[104:105], 14, v[140:141]
	v_cvt_pk_bf16_f32 v108, v108, s0
	v_lshl_add_u64 v[104:105], v[150:151], 0, v[104:105]
	v_ashrrev_i32_e32 v139, 31, v138
	global_store_short v[104:105], v108, off
	v_lshlrev_b64 v[104:105], 14, v[138:139]
	v_cvt_pk_bf16_f32 v108, v157, s0
	v_lshl_add_u64 v[104:105], v[150:151], 0, v[104:105]
	v_ashrrev_i32_e32 v137, 31, v136
	global_store_short v[104:105], v108, off
	v_lshlrev_b64 v[104:105], 14, v[136:137]
	v_cvt_pk_bf16_f32 v108, v109, s0
	v_lshl_add_u64 v[104:105], v[150:151], 0, v[104:105]
	v_ashrrev_i32_e32 v135, 31, v134
	global_store_short v[104:105], v108, off
	v_lshlrev_b64 v[104:105], 14, v[134:135]
	v_cvt_pk_bf16_f32 v108, v110, s0
	v_lshl_add_u64 v[104:105], v[150:151], 0, v[104:105]
	v_ashrrev_i32_e32 v133, 31, v132
	global_store_short v[104:105], v108, off
	v_lshlrev_b64 v[104:105], 14, v[132:133]
	v_cvt_pk_bf16_f32 v106, v106, s0
	v_lshl_add_u64 v[104:105], v[150:151], 0, v[104:105]
	v_ashrrev_i32_e32 v131, 31, v130
	global_store_short v[104:105], v106, off
	v_lshlrev_b64 v[104:105], 14, v[130:131]
	v_cvt_pk_bf16_f32 v106, v111, s0
	v_lshl_add_u64 v[104:105], v[150:151], 0, v[104:105]
	v_ashrrev_i32_e32 v121, 31, v120
	global_store_short v[104:105], v106, off
	v_lshlrev_b64 v[104:105], 14, v[120:121]
	v_cvt_pk_bf16_f32 v106, v107, s0
	v_lshl_add_u64 v[104:105], v[150:151], 0, v[104:105]
	global_store_short v[104:105], v106, off

.LBB0_1176:
	s_or_b64 exec, exec, s[6:7]
	v_or_b32_e32 v98, 32, v128
	v_lshlrev_b32_e32 v96, 1, v98
	v_ashrrev_i32_e32 v97, 31, v96
	v_lshl_add_u64 v[96:97], v[96:97], 2, s[62:63]
	v_add_co_u32_e32 v96, vcc, 0xe000, v96
	s_movk_i32 s6, 0x1faf
	s_nop 0
	v_addc_co_u32_e32 v97, vcc, 0, v97, vcc
	s_nop 1
	v_mov_b32_e32 v96, v243
	v_fmamk_f32 v96, v96, 0x3b800000, v174
	v_mul_f32_e32 v97, 0x4b800000, v96
	v_cmp_gt_f32_e32 vcc, s79, v96
	s_nop 1
	v_cndmask_b32_e32 v96, v96, v97, vcc
	v_rsq_f32_e32 v99, v96
	v_bitop3_b32 v96, v128, s6, 32 bitop3:0xc8
	v_lshlrev_b32_e32 v168, 1, v96
	v_lshl_add_u64 v[96:97], s[16:17], 0, v[168:169]
	v_mul_f32_e32 v100, 0x45800000, v99
	v_cndmask_b32_e32 v100, v99, v100, vcc
	v_pk_mul_f32 v[94:95], v[94:95], v[100:101] op_sel_hi:[1,0]
	v_pk_mul_f32 v[102:103], v[92:93], v[100:101] op_sel_hi:[1,0]
	v_pk_mul_f32 v[90:91], v[90:91], v[100:101] op_sel_hi:[1,0]
	v_pk_mul_f32 v[92:93], v[88:89], v[100:101] op_sel_hi:[1,0]
	s_and_saveexec_b64 s[6:7], s[2:3]
	s_xor_b64 s[6:7], exec, s[6:7]
	s_cbranch_execz .LBB0_1178
	v_lshlrev_b64 v[88:89], 14, v[142:143]
	v_cvt_pk_bf16_f32 v99, v102, s0
	v_lshl_add_u64 v[88:89], v[96:97], 0, v[88:89]
	v_ashrrev_i32_e32 v141, 31, v140
	global_store_short v[88:89], v99, off
	v_lshlrev_b64 v[88:89], 14, v[140:141]
	v_cvt_pk_bf16_f32 v92, v92, s0
	v_lshl_add_u64 v[88:89], v[96:97], 0, v[88:89]
	v_ashrrev_i32_e32 v139, 31, v138
	global_store_short v[88:89], v92, off
	v_lshlrev_b64 v[88:89], 14, v[138:139]
	v_cvt_pk_bf16_f32 v92, v103, s0
	v_lshl_add_u64 v[88:89], v[96:97], 0, v[88:89]
	v_ashrrev_i32_e32 v137, 31, v136
	global_store_short v[88:89], v92, off
	v_lshlrev_b64 v[88:89], 14, v[136:137]
	v_cvt_pk_bf16_f32 v92, v93, s0
	v_lshl_add_u64 v[88:89], v[96:97], 0, v[88:89]
	v_ashrrev_i32_e32 v135, 31, v134
	global_store_short v[88:89], v92, off
	v_lshlrev_b64 v[88:89], 14, v[134:135]
	v_cvt_pk_bf16_f32 v92, v94, s0
	v_lshl_add_u64 v[88:89], v[96:97], 0, v[88:89]
	v_ashrrev_i32_e32 v133, 31, v132
	global_store_short v[88:89], v92, off
	v_lshlrev_b64 v[88:89], 14, v[132:133]
	v_cvt_pk_bf16_f32 v90, v90, s0
	v_lshl_add_u64 v[88:89], v[96:97], 0, v[88:89]
	v_ashrrev_i32_e32 v131, 31, v130
	global_store_short v[88:89], v90, off
	v_lshlrev_b64 v[88:89], 14, v[130:131]
	v_cvt_pk_bf16_f32 v90, v95, s0
	v_lshl_add_u64 v[88:89], v[96:97], 0, v[88:89]
	v_ashrrev_i32_e32 v121, 31, v120
	global_store_short v[88:89], v90, off
	v_lshlrev_b64 v[88:89], 14, v[120:121]
	v_cvt_pk_bf16_f32 v90, v91, s0
	v_lshl_add_u64 v[88:89], v[96:97], 0, v[88:89]
	global_store_short v[88:89], v90, off

.LBB0_1184:
	s_or_b64 exec, exec, s[6:7]
	v_or_b32_e32 v82, 48, v128
	v_lshlrev_b32_e32 v80, 1, v82
	v_ashrrev_i32_e32 v81, 31, v80
	v_lshl_add_u64 v[80:81], v[80:81], 2, s[62:63]
	v_add_co_u32_e32 v80, vcc, 0xe000, v80
	s_movk_i32 s6, 0x1fbf
	s_nop 0
	v_addc_co_u32_e32 v81, vcc, 0, v81, vcc
	s_nop 1
	v_mov_b32_e32 v80, v244
	v_fmamk_f32 v80, v80, 0x3b800000, v174
	v_mul_f32_e32 v81, 0x4b800000, v80
	v_cmp_gt_f32_e32 vcc, s79, v80
	s_nop 1
	v_cndmask_b32_e32 v80, v80, v81, vcc
	v_rsq_f32_e32 v83, v80
	v_bitop3_b32 v80, v128, s6, 48 bitop3:0xc8
	v_lshlrev_b32_e32 v168, 1, v80
	v_lshl_add_u64 v[80:81], s[16:17], 0, v[168:169]
	v_mul_f32_e32 v84, 0x45800000, v83
	v_cndmask_b32_e32 v84, v83, v84, vcc
	v_pk_mul_f32 v[78:79], v[78:79], v[84:85] op_sel_hi:[1,0]
	v_pk_mul_f32 v[86:87], v[76:77], v[84:85] op_sel_hi:[1,0]
	v_pk_mul_f32 v[74:75], v[74:75], v[84:85] op_sel_hi:[1,0]
	v_pk_mul_f32 v[76:77], v[72:73], v[84:85] op_sel_hi:[1,0]
	s_and_saveexec_b64 s[6:7], s[2:3]
	s_xor_b64 s[6:7], exec, s[6:7]
	s_cbranch_execz .LBB0_1186
	v_lshlrev_b64 v[72:73], 14, v[142:143]
	v_cvt_pk_bf16_f32 v83, v86, s0
	v_lshl_add_u64 v[72:73], v[80:81], 0, v[72:73]
	v_ashrrev_i32_e32 v141, 31, v140
	global_store_short v[72:73], v83, off
	v_lshlrev_b64 v[72:73], 14, v[140:141]
	v_cvt_pk_bf16_f32 v76, v76, s0
	v_lshl_add_u64 v[72:73], v[80:81], 0, v[72:73]
	v_ashrrev_i32_e32 v139, 31, v138
	global_store_short v[72:73], v76, off
	v_lshlrev_b64 v[72:73], 14, v[138:139]
	v_cvt_pk_bf16_f32 v76, v87, s0
	v_lshl_add_u64 v[72:73], v[80:81], 0, v[72:73]
	v_ashrrev_i32_e32 v137, 31, v136
	global_store_short v[72:73], v76, off
	v_lshlrev_b64 v[72:73], 14, v[136:137]
	v_cvt_pk_bf16_f32 v76, v77, s0
	v_lshl_add_u64 v[72:73], v[80:81], 0, v[72:73]
	v_ashrrev_i32_e32 v135, 31, v134
	global_store_short v[72:73], v76, off
	v_lshlrev_b64 v[72:73], 14, v[134:135]
	v_cvt_pk_bf16_f32 v76, v78, s0
	v_lshl_add_u64 v[72:73], v[80:81], 0, v[72:73]
	v_ashrrev_i32_e32 v133, 31, v132
	global_store_short v[72:73], v76, off
	v_lshlrev_b64 v[72:73], 14, v[132:133]
	v_cvt_pk_bf16_f32 v74, v74, s0
	v_lshl_add_u64 v[72:73], v[80:81], 0, v[72:73]
	v_ashrrev_i32_e32 v131, 31, v130
	global_store_short v[72:73], v74, off
	v_lshlrev_b64 v[72:73], 14, v[130:131]
	v_cvt_pk_bf16_f32 v74, v79, s0
	v_lshl_add_u64 v[72:73], v[80:81], 0, v[72:73]
	v_ashrrev_i32_e32 v121, 31, v120
	global_store_short v[72:73], v74, off
	v_lshlrev_b64 v[72:73], 14, v[120:121]
	v_cvt_pk_bf16_f32 v74, v75, s0
	v_lshl_add_u64 v[72:73], v[80:81], 0, v[72:73]
	global_store_short v[72:73], v74, off

.LBB0_1192:
	s_or_b64 exec, exec, s[6:7]
	v_or_b32_e32 v66, 64, v128
	v_lshlrev_b32_e32 v64, 1, v66
	v_ashrrev_i32_e32 v65, 31, v64
	v_lshl_add_u64 v[64:65], v[64:65], 2, s[62:63]
	v_add_co_u32_e32 v64, vcc, 0xe000, v64
	s_movk_i32 s6, 0x1fcf
	s_nop 0
	v_addc_co_u32_e32 v65, vcc, 0, v65, vcc
	s_nop 1
	v_mov_b32_e32 v64, v245
	v_fmamk_f32 v64, v64, 0x3b800000, v174
	v_mul_f32_e32 v65, 0x4b800000, v64
	v_cmp_gt_f32_e32 vcc, s79, v64
	s_nop 1
	v_cndmask_b32_e32 v64, v64, v65, vcc
	v_rsq_f32_e32 v67, v64
	v_bitop3_b32 v64, v128, s6, 64 bitop3:0xc8
	v_lshlrev_b32_e32 v168, 1, v64
	v_lshl_add_u64 v[64:65], s[16:17], 0, v[168:169]
	v_mul_f32_e32 v68, 0x45800000, v67
	v_cndmask_b32_e32 v68, v67, v68, vcc
	v_pk_mul_f32 v[62:63], v[62:63], v[68:69] op_sel_hi:[1,0]
	v_pk_mul_f32 v[70:71], v[60:61], v[68:69] op_sel_hi:[1,0]
	v_pk_mul_f32 v[58:59], v[58:59], v[68:69] op_sel_hi:[1,0]
	v_pk_mul_f32 v[60:61], v[56:57], v[68:69] op_sel_hi:[1,0]
	s_and_saveexec_b64 s[6:7], s[2:3]
	s_xor_b64 s[6:7], exec, s[6:7]
	s_cbranch_execz .LBB0_1194
	v_lshlrev_b64 v[56:57], 14, v[142:143]
	v_cvt_pk_bf16_f32 v67, v70, s0
	v_lshl_add_u64 v[56:57], v[64:65], 0, v[56:57]
	v_ashrrev_i32_e32 v141, 31, v140
	global_store_short v[56:57], v67, off
	v_lshlrev_b64 v[56:57], 14, v[140:141]
	v_cvt_pk_bf16_f32 v60, v60, s0
	v_lshl_add_u64 v[56:57], v[64:65], 0, v[56:57]
	v_ashrrev_i32_e32 v139, 31, v138
	global_store_short v[56:57], v60, off
	v_lshlrev_b64 v[56:57], 14, v[138:139]
	v_cvt_pk_bf16_f32 v60, v71, s0
	v_lshl_add_u64 v[56:57], v[64:65], 0, v[56:57]
	v_ashrrev_i32_e32 v137, 31, v136
	global_store_short v[56:57], v60, off
	v_lshlrev_b64 v[56:57], 14, v[136:137]
	v_cvt_pk_bf16_f32 v60, v61, s0
	v_lshl_add_u64 v[56:57], v[64:65], 0, v[56:57]
	v_ashrrev_i32_e32 v135, 31, v134
	global_store_short v[56:57], v60, off
	v_lshlrev_b64 v[56:57], 14, v[134:135]
	v_cvt_pk_bf16_f32 v60, v62, s0
	v_lshl_add_u64 v[56:57], v[64:65], 0, v[56:57]
	v_ashrrev_i32_e32 v133, 31, v132
	global_store_short v[56:57], v60, off
	v_lshlrev_b64 v[56:57], 14, v[132:133]
	v_cvt_pk_bf16_f32 v58, v58, s0
	v_lshl_add_u64 v[56:57], v[64:65], 0, v[56:57]
	v_ashrrev_i32_e32 v131, 31, v130
	global_store_short v[56:57], v58, off
	v_lshlrev_b64 v[56:57], 14, v[130:131]
	v_cvt_pk_bf16_f32 v58, v63, s0
	v_lshl_add_u64 v[56:57], v[64:65], 0, v[56:57]
	v_ashrrev_i32_e32 v121, 31, v120
	global_store_short v[56:57], v58, off
	v_lshlrev_b64 v[56:57], 14, v[120:121]
	v_cvt_pk_bf16_f32 v58, v59, s0
	v_lshl_add_u64 v[56:57], v[64:65], 0, v[56:57]
	global_store_short v[56:57], v58, off

.LBB0_1200:
	s_or_b64 exec, exec, s[6:7]
	v_or_b32_e32 v50, 0x50, v128
	v_lshlrev_b32_e32 v48, 1, v50
	v_ashrrev_i32_e32 v49, 31, v48
	v_lshl_add_u64 v[48:49], v[48:49], 2, s[62:63]
	v_add_co_u32_e32 v48, vcc, 0xe000, v48
	s_movk_i32 s6, 0x1fdf
	s_nop 0
	v_addc_co_u32_e32 v49, vcc, 0, v49, vcc
	s_nop 1
	v_mov_b32_e32 v48, v246
	v_fmamk_f32 v48, v48, 0x3b800000, v174
	v_mul_f32_e32 v49, 0x4b800000, v48
	v_cmp_gt_f32_e32 vcc, s79, v48
	s_nop 1
	v_cndmask_b32_e32 v48, v48, v49, vcc
	v_rsq_f32_e32 v51, v48
	v_bitop3_b32 v48, v128, s6, v176 bitop3:0xc8
	v_lshlrev_b32_e32 v168, 1, v48
	v_lshl_add_u64 v[48:49], s[16:17], 0, v[168:169]
	v_mul_f32_e32 v52, 0x45800000, v51
	v_cndmask_b32_e32 v52, v51, v52, vcc
	v_pk_mul_f32 v[46:47], v[46:47], v[52:53] op_sel_hi:[1,0]
	v_pk_mul_f32 v[54:55], v[44:45], v[52:53] op_sel_hi:[1,0]
	v_pk_mul_f32 v[42:43], v[42:43], v[52:53] op_sel_hi:[1,0]
	v_pk_mul_f32 v[44:45], v[40:41], v[52:53] op_sel_hi:[1,0]
	s_and_saveexec_b64 s[6:7], s[2:3]
	s_xor_b64 s[6:7], exec, s[6:7]
	s_cbranch_execz .LBB0_1202
	v_lshlrev_b64 v[40:41], 14, v[142:143]
	v_cvt_pk_bf16_f32 v51, v54, s0
	v_lshl_add_u64 v[40:41], v[48:49], 0, v[40:41]
	v_ashrrev_i32_e32 v141, 31, v140
	global_store_short v[40:41], v51, off
	v_lshlrev_b64 v[40:41], 14, v[140:141]
	v_cvt_pk_bf16_f32 v44, v44, s0
	v_lshl_add_u64 v[40:41], v[48:49], 0, v[40:41]
	v_ashrrev_i32_e32 v139, 31, v138
	global_store_short v[40:41], v44, off
	v_lshlrev_b64 v[40:41], 14, v[138:139]
	v_cvt_pk_bf16_f32 v44, v55, s0
	v_lshl_add_u64 v[40:41], v[48:49], 0, v[40:41]
	v_ashrrev_i32_e32 v137, 31, v136
	global_store_short v[40:41], v44, off
	v_lshlrev_b64 v[40:41], 14, v[136:137]
	v_cvt_pk_bf16_f32 v44, v45, s0
	v_lshl_add_u64 v[40:41], v[48:49], 0, v[40:41]
	v_ashrrev_i32_e32 v135, 31, v134
	global_store_short v[40:41], v44, off
	v_lshlrev_b64 v[40:41], 14, v[134:135]
	v_cvt_pk_bf16_f32 v44, v46, s0
	v_lshl_add_u64 v[40:41], v[48:49], 0, v[40:41]
	v_ashrrev_i32_e32 v133, 31, v132
	global_store_short v[40:41], v44, off
	v_lshlrev_b64 v[40:41], 14, v[132:133]
	v_cvt_pk_bf16_f32 v42, v42, s0
	v_lshl_add_u64 v[40:41], v[48:49], 0, v[40:41]
	v_ashrrev_i32_e32 v131, 31, v130
	global_store_short v[40:41], v42, off
	v_lshlrev_b64 v[40:41], 14, v[130:131]
	v_cvt_pk_bf16_f32 v42, v47, s0
	v_lshl_add_u64 v[40:41], v[48:49], 0, v[40:41]
	v_ashrrev_i32_e32 v121, 31, v120
	global_store_short v[40:41], v42, off
	v_lshlrev_b64 v[40:41], 14, v[120:121]
	v_cvt_pk_bf16_f32 v42, v43, s0
	v_lshl_add_u64 v[40:41], v[48:49], 0, v[40:41]
	global_store_short v[40:41], v42, off

.LBB0_1208:
	s_or_b64 exec, exec, s[6:7]
	v_or_b32_e32 v34, 0x60, v128
	v_lshlrev_b32_e32 v32, 1, v34
	v_ashrrev_i32_e32 v33, 31, v32
	v_lshl_add_u64 v[32:33], v[32:33], 2, s[62:63]
	v_add_co_u32_e32 v32, vcc, 0xe000, v32
	s_movk_i32 s6, 0x1fef
	s_nop 0
	v_addc_co_u32_e32 v33, vcc, 0, v33, vcc
	s_nop 1
	v_mov_b32_e32 v32, v247
	v_fmamk_f32 v32, v32, 0x3b800000, v174
	v_mul_f32_e32 v33, 0x4b800000, v32
	v_cmp_gt_f32_e32 vcc, s79, v32
	s_nop 1
	v_cndmask_b32_e32 v32, v32, v33, vcc
	v_rsq_f32_e32 v35, v32
	v_bitop3_b32 v32, v128, s6, v177 bitop3:0xc8
	v_lshlrev_b32_e32 v168, 1, v32
	v_lshl_add_u64 v[32:33], s[16:17], 0, v[168:169]
	v_mul_f32_e32 v36, 0x45800000, v35
	v_cndmask_b32_e32 v36, v35, v36, vcc
	v_pk_mul_f32 v[30:31], v[30:31], v[36:37] op_sel_hi:[1,0]
	v_pk_mul_f32 v[38:39], v[28:29], v[36:37] op_sel_hi:[1,0]
	v_pk_mul_f32 v[26:27], v[26:27], v[36:37] op_sel_hi:[1,0]
	v_pk_mul_f32 v[28:29], v[24:25], v[36:37] op_sel_hi:[1,0]
	s_and_saveexec_b64 s[6:7], s[2:3]
	s_xor_b64 s[6:7], exec, s[6:7]
	s_cbranch_execz .LBB0_1210
	v_lshlrev_b64 v[24:25], 14, v[142:143]
	v_cvt_pk_bf16_f32 v35, v38, s0
	v_lshl_add_u64 v[24:25], v[32:33], 0, v[24:25]
	v_ashrrev_i32_e32 v141, 31, v140
	global_store_short v[24:25], v35, off
	v_lshlrev_b64 v[24:25], 14, v[140:141]
	v_cvt_pk_bf16_f32 v28, v28, s0
	v_lshl_add_u64 v[24:25], v[32:33], 0, v[24:25]
	v_ashrrev_i32_e32 v139, 31, v138
	global_store_short v[24:25], v28, off
	v_lshlrev_b64 v[24:25], 14, v[138:139]
	v_cvt_pk_bf16_f32 v28, v39, s0
	v_lshl_add_u64 v[24:25], v[32:33], 0, v[24:25]
	v_ashrrev_i32_e32 v137, 31, v136
	global_store_short v[24:25], v28, off
	v_lshlrev_b64 v[24:25], 14, v[136:137]
	v_cvt_pk_bf16_f32 v28, v29, s0
	v_lshl_add_u64 v[24:25], v[32:33], 0, v[24:25]
	v_ashrrev_i32_e32 v135, 31, v134
	global_store_short v[24:25], v28, off
	v_lshlrev_b64 v[24:25], 14, v[134:135]
	v_cvt_pk_bf16_f32 v28, v30, s0
	v_lshl_add_u64 v[24:25], v[32:33], 0, v[24:25]
	v_ashrrev_i32_e32 v133, 31, v132
	global_store_short v[24:25], v28, off
	v_lshlrev_b64 v[24:25], 14, v[132:133]
	v_cvt_pk_bf16_f32 v26, v26, s0
	v_lshl_add_u64 v[24:25], v[32:33], 0, v[24:25]
	v_ashrrev_i32_e32 v131, 31, v130
	global_store_short v[24:25], v26, off
	v_lshlrev_b64 v[24:25], 14, v[130:131]
	v_cvt_pk_bf16_f32 v26, v31, s0
	v_lshl_add_u64 v[24:25], v[32:33], 0, v[24:25]
	v_ashrrev_i32_e32 v121, 31, v120
	global_store_short v[24:25], v26, off
	v_lshlrev_b64 v[24:25], 14, v[120:121]
	v_cvt_pk_bf16_f32 v26, v27, s0
	v_lshl_add_u64 v[24:25], v[32:33], 0, v[24:25]
	global_store_short v[24:25], v26, off

.LBB0_1216:
	s_or_b64 exec, exec, s[6:7]
	v_or_b32_e32 v18, 0x70, v128
	v_lshlrev_b32_e32 v16, 1, v18
	v_ashrrev_i32_e32 v17, 31, v16
	v_lshl_add_u64 v[16:17], v[16:17], 2, s[62:63]
	v_add_co_u32_e32 v16, vcc, 0xe000, v16
	s_movk_i32 s6, 0x1fff
	s_nop 0
	v_addc_co_u32_e32 v17, vcc, 0, v17, vcc
	s_nop 1
	v_mov_b32_e32 v16, v248
	v_fmamk_f32 v16, v16, 0x3b800000, v174
	v_mul_f32_e32 v17, 0x4b800000, v16
	v_cmp_gt_f32_e32 vcc, s79, v16
	s_nop 1
	v_cndmask_b32_e32 v16, v16, v17, vcc
	v_rsq_f32_e32 v19, v16
	v_bitop3_b32 v16, v128, s6, v178 bitop3:0xc8
	v_lshlrev_b32_e32 v168, 1, v16
	v_lshl_add_u64 v[16:17], s[16:17], 0, v[168:169]
	v_mul_f32_e32 v20, 0x45800000, v19
	v_cndmask_b32_e32 v20, v19, v20, vcc
	v_pk_mul_f32 v[14:15], v[14:15], v[20:21] op_sel_hi:[1,0]
	v_pk_mul_f32 v[22:23], v[12:13], v[20:21] op_sel_hi:[1,0]
	v_pk_mul_f32 v[10:11], v[10:11], v[20:21] op_sel_hi:[1,0]
	v_pk_mul_f32 v[12:13], v[8:9], v[20:21] op_sel_hi:[1,0]
	s_and_saveexec_b64 s[6:7], s[2:3]
	s_xor_b64 s[6:7], exec, s[6:7]
	s_cbranch_execz .LBB0_1218
	v_lshlrev_b64 v[8:9], 14, v[142:143]
	v_cvt_pk_bf16_f32 v19, v22, s0
	v_lshl_add_u64 v[8:9], v[16:17], 0, v[8:9]
	v_ashrrev_i32_e32 v141, 31, v140
	global_store_short v[8:9], v19, off
	v_lshlrev_b64 v[8:9], 14, v[140:141]
	v_cvt_pk_bf16_f32 v12, v12, s0
	v_lshl_add_u64 v[8:9], v[16:17], 0, v[8:9]
	v_ashrrev_i32_e32 v139, 31, v138
	global_store_short v[8:9], v12, off
	v_lshlrev_b64 v[8:9], 14, v[138:139]
	v_cvt_pk_bf16_f32 v12, v23, s0
	v_lshl_add_u64 v[8:9], v[16:17], 0, v[8:9]
	v_ashrrev_i32_e32 v137, 31, v136
	global_store_short v[8:9], v12, off
	v_lshlrev_b64 v[8:9], 14, v[136:137]
	v_cvt_pk_bf16_f32 v12, v13, s0
	v_lshl_add_u64 v[8:9], v[16:17], 0, v[8:9]
	v_ashrrev_i32_e32 v135, 31, v134
	global_store_short v[8:9], v12, off
	v_lshlrev_b64 v[8:9], 14, v[134:135]
	v_cvt_pk_bf16_f32 v12, v14, s0
	v_lshl_add_u64 v[8:9], v[16:17], 0, v[8:9]
	v_ashrrev_i32_e32 v133, 31, v132
	global_store_short v[8:9], v12, off
	v_lshlrev_b64 v[8:9], 14, v[132:133]
	v_cvt_pk_bf16_f32 v10, v10, s0
	v_lshl_add_u64 v[8:9], v[16:17], 0, v[8:9]
	v_ashrrev_i32_e32 v131, 31, v130
	global_store_short v[8:9], v10, off
	v_lshlrev_b64 v[8:9], 14, v[130:131]
	v_cvt_pk_bf16_f32 v10, v15, s0
	v_lshl_add_u64 v[8:9], v[16:17], 0, v[8:9]
	v_ashrrev_i32_e32 v121, 31, v120
	global_store_short v[8:9], v10, off
	v_lshlrev_b64 v[8:9], 14, v[120:121]
	v_cvt_pk_bf16_f32 v10, v11, s0
	v_lshl_add_u64 v[8:9], v[16:17], 0, v[8:9]
	global_store_short v[8:9], v10, off

.LBB0_1234:
	v_or_b32_e32 v168, v187, v171
	v_lshlrev_b32_e32 v88, 1, v168
	v_mov_b32_e32 v89, v169
	v_lshl_add_u64 v[88:89], v[88:89], 2, s[22:23]
	v_mov_b64_e32 v[250:251], v[88:89]
	global_load_dword v88, v[88:89], off
	v_lshl_add_u64 v[92:93], v[168:169], 2, s[24:25]
	global_load_dword v242, v[250:251], off offset:128
	global_load_dword v243, v[250:251], off offset:256
	global_load_dword v244, v[250:251], off offset:384
	global_load_dword v245, v[92:93], off offset:64
	global_load_dword v246, v[92:93], off offset:128
	global_load_dword v247, v[92:93], off offset:192
	s_waitcnt vmcnt(11)
	v_lshrrev_b32_e32 v109, 4, v188
	v_lshlrev_b32_e32 v104, 2, v109
	v_cmp_lt_i32_e64 s[6:7], 5, v186
	v_cvt_f32_ubyte0_e32 v107, v104
	v_or_b32_e32 v108, 1, v104
	v_or_b32_e32 v105, 2, v104
	v_or_b32_e32 v106, 3, v104
	s_waitcnt vmcnt(0)
	v_fmamk_f32 v88, v88, 0x3aaaaaab, v174
	v_cmp_gt_f32_e32 vcc, s79, v88
	v_mul_f32_e32 v89, 0x4b800000, v88
	s_nop 0
	v_cndmask_b32_e32 v88, v88, v89, vcc
	v_rsq_f32_e32 v88, v88
	s_nop 0
	v_mul_f32_e32 v89, 0x45800000, v88
	v_cndmask_b32_e32 v94, v88, v89, vcc
	global_load_dword v88, v[92:93], off
	v_pk_mul_f32 v[90:91], v[166:167], v[94:95] op_sel_hi:[1,0]
	v_pk_mul_f32 v[100:101], v[162:163], v[94:95] op_sel_hi:[1,0]
	v_pk_mul_f32 v[102:103], v[160:161], v[94:95] op_sel_hi:[1,0]
	s_waitcnt vmcnt(0)
	v_cvt_f32_i32_e32 v110, v88
	v_pk_mul_f32 v[88:89], v[164:165], v[94:95] op_sel_hi:[1,0]
	s_and_saveexec_b64 s[2:3], s[6:7]
	s_cbranch_execz .LBB0_1236
	v_mul_f32_e32 v95, 0xbf549a78, v107
	v_cmp_gt_f32_e32 vcc, s86, v95
	v_cvt_f32_ubyte0_e32 v97, v108
	v_mul_f32_e32 v98, 0xbf549a78, v97
	v_cndmask_b32_e32 v96, 0, v180, vcc
	v_fmac_f32_e32 v96, 0xbf549a78, v107
	v_exp_f32_e32 v96, v96
	v_cndmask_b32_e32 v95, 0, v179, vcc
	v_cmp_gt_f32_e32 vcc, s86, v98
	v_cvt_f32_ubyte0_e32 v114, v106
	v_ldexp_f32 v95, v96, v95
	v_mul_f32_e32 v95, v95, v110
	v_mul_f32_e32 v96, 0.15915494, v95
	v_rndne_f32_e32 v96, v96
	v_fma_f32 v99, v95, 0.15915494, -v96
	v_fmac_f32_e32 v99, 0x31dc9c88, v95
	v_cndmask_b32_e32 v95, 0, v180, vcc
	v_fmac_f32_e32 v95, 0xbf549a78, v97
	v_exp_f32_e32 v95, v95
	v_cndmask_b32_e32 v97, 0, v179, vcc
	v_sin_f32_e32 v96, v99
	v_cos_f32_e32 v98, v99
	v_ldexp_f32 v95, v95, v97
	v_mul_f32_e32 v95, v95, v110
	v_mul_f32_e32 v97, 0.15915494, v95
	v_rndne_f32_e32 v97, v97
	v_fma_f32 v99, v95, 0.15915494, -v97
	v_fmac_f32_e32 v99, 0x31dc9c88, v95
	v_cvt_f32_ubyte0_e32 v95, v105
	v_mul_f32_e32 v111, 0xbf549a78, v95
	v_cmp_gt_f32_e32 vcc, s86, v111
	v_mul_f32_e32 v115, 0xbf549a78, v114
	v_sin_f32_e32 v97, v99
	v_cndmask_b32_e32 v111, 0, v180, vcc
	v_fmac_f32_e32 v111, 0xbf549a78, v95
	v_exp_f32_e32 v95, v111
	v_cndmask_b32_e32 v111, 0, v179, vcc
	v_cmp_gt_f32_e32 vcc, s86, v115
	v_cos_f32_e32 v99, v99
	v_ldexp_f32 v95, v95, v111
	v_cndmask_b32_e32 v115, 0, v180, vcc
	v_fmac_f32_e32 v115, 0xbf549a78, v114
	v_exp_f32_e32 v115, v115
	v_cndmask_b32_e32 v117, 0, v179, vcc
	v_mul_f32_e32 v95, v95, v110
	v_mul_f32_e32 v111, 0.15915494, v95
	v_ldexp_f32 v115, v115, v117
	v_mul_f32_e32 v115, v115, v110
	v_rndne_f32_e32 v111, v111
	v_mul_f32_e32 v117, 0.15915494, v115
	v_fma_f32 v111, v95, 0.15915494, -v111
	v_rndne_f32_e32 v117, v117
	v_fmac_f32_e32 v111, 0x31dc9c88, v95
	v_fma_f32 v117, v115, 0.15915494, -v117
	v_sin_f32_e32 v95, v111
	v_cos_f32_e32 v111, v111
	v_fmac_f32_e32 v117, 0x31dc9c88, v115
	v_sin_f32_e32 v119, v117
	v_cos_f32_e32 v118, v117
	v_mul_f32_e32 v116, v95, v100
	v_mul_f32_e32 v120, v111, v100
	v_mov_b32_e32 v100, v91
	v_mul_f32_e32 v114, v111, v90
	v_mul_f32_e32 v122, v95, v90
	v_pk_mul_f32 v[90:91], v[118:119], v[100:101]
	v_pk_mul_f32 v[112:113], v[96:97], v[102:103]
	v_mov_b32_e32 v115, v90
	v_mov_b32_e32 v117, v91
	v_mov_b32_e32 v90, v119
	v_mov_b32_e32 v91, v118
	v_pk_mul_f32 v[90:91], v[90:91], v[100:101]
	v_pk_mul_f32 v[102:103], v[98:99], v[102:103]
	v_mov_b32_e32 v123, v90
	v_mov_b32_e32 v121, v91
	v_pk_fma_f32 v[98:99], v[98:99], v[88:89], v[112:113] neg_lo:[0,0,1] neg_hi:[0,0,1]
	v_pk_add_f32 v[90:91], v[114:115], v[116:117] neg_lo:[0,1] neg_hi:[0,1]
	v_pk_fma_f32 v[102:103], v[96:97], v[88:89], v[102:103]
	v_pk_add_f32 v[100:101], v[122:123], v[120:121]
	v_mov_b32_e32 v88, v98
	v_mov_b32_e32 v89, v99

.LBB0_1258:
	s_nop 0
	v_or_b32_e32 v72, 16, v168
	v_lshlrev_b32_e32 v74, 1, v72
	v_mov_b32_e32 v75, v169
	v_lshl_add_u64 v[74:75], v[74:75], 2, s[22:23]
	v_mov_b32_e32 v73, v242
	s_nop 0
	v_mov_b32_e32 v74, v245
	v_fmamk_f32 v73, v73, 0x3aaaaaab, v174
	v_mul_f32_e32 v75, 0x4b800000, v73
	v_cmp_gt_f32_e32 vcc, s79, v73
	s_nop 0
	v_cvt_f32_i32_e32 v77, v74
	v_cndmask_b32_e32 v73, v73, v75, vcc
	v_rsq_f32_e32 v73, v73
	s_nop 0
	v_mul_f32_e32 v74, 0x45800000, v73
	v_cndmask_b32_e32 v74, v73, v74, vcc
	v_pk_mul_f32 v[82:83], v[70:71], v[74:75] op_sel_hi:[1,0]
	v_pk_mul_f32 v[78:79], v[68:69], v[74:75] op_sel_hi:[1,0]
	v_pk_mul_f32 v[80:81], v[66:67], v[74:75] op_sel_hi:[1,0]
	v_pk_mul_f32 v[66:67], v[64:65], v[74:75] op_sel_hi:[1,0]
	s_and_saveexec_b64 s[76:77], s[6:7]
	s_cbranch_execz .LBB0_1260
	v_mul_f32_e32 v64, 0xbf549a78, v107
	v_cmp_gt_f32_e32 vcc, s86, v64
	v_cvt_f32_ubyte0_e32 v68, v108
	v_mul_f32_e32 v69, 0xbf549a78, v68
	v_cndmask_b32_e32 v65, 0, v180, vcc
	v_fmac_f32_e32 v65, 0xbf549a78, v107
	v_exp_f32_e32 v65, v65
	v_cndmask_b32_e32 v64, 0, v179, vcc
	v_cmp_gt_f32_e32 vcc, s86, v69
	v_cvt_f32_ubyte0_e32 v70, v105
	v_ldexp_f32 v64, v65, v64
	v_mul_f32_e32 v64, v64, v77
	v_mul_f32_e32 v65, 0.15915494, v64
	v_rndne_f32_e32 v65, v65
	v_fma_f32 v65, v64, 0.15915494, -v65
	v_fmac_f32_e32 v65, 0x31dc9c88, v64
	v_cndmask_b32_e32 v64, 0, v180, vcc
	v_fmac_f32_e32 v64, 0xbf549a78, v68
	v_mul_f32_e32 v71, 0xbf549a78, v70
	v_cvt_f32_ubyte0_e32 v85, v106
	v_exp_f32_e32 v69, v64
	v_sin_f32_e32 v64, v65
	v_cos_f32_e32 v68, v65
	v_cndmask_b32_e32 v65, 0, v179, vcc
	v_cmp_gt_f32_e32 vcc, s86, v71
	v_mul_f32_e32 v86, 0xbf549a78, v85
	v_ldexp_f32 v65, v69, v65
	v_cndmask_b32_e32 v71, 0, v180, vcc
	v_cndmask_b32_e32 v75, 0, v179, vcc
	v_cmp_gt_f32_e32 vcc, s86, v86
	v_fmac_f32_e32 v71, 0xbf549a78, v70
	v_exp_f32_e32 v73, v71
	v_cndmask_b32_e32 v86, 0, v180, vcc
	v_fmac_f32_e32 v86, 0xbf549a78, v85
	v_exp_f32_e32 v85, v86
	v_ldexp_f32 v73, v73, v75
	v_cndmask_b32_e32 v87, 0, v179, vcc
	v_mul_f32_e32 v73, v73, v77
	v_ldexp_f32 v85, v85, v87
	v_mul_f32_e32 v75, 0.15915494, v73
	v_mul_f32_e32 v85, v85, v77
	v_rndne_f32_e32 v75, v75
	v_mul_f32_e32 v87, 0.15915494, v85
	v_mul_f32_e32 v65, v65, v77
	v_fma_f32 v75, v73, 0.15915494, -v75
	v_rndne_f32_e32 v87, v87
	v_mul_f32_e32 v69, 0.15915494, v65
	v_fmac_f32_e32 v75, 0x31dc9c88, v73
	v_fma_f32 v87, v85, 0.15915494, -v87
	v_rndne_f32_e32 v69, v69
	v_sin_f32_e32 v73, v75
	v_cos_f32_e32 v75, v75
	v_fmac_f32_e32 v87, 0x31dc9c88, v85
	v_fma_f32 v69, v65, 0.15915494, -v69
	v_sin_f32_e32 v91, v87
	v_cos_f32_e32 v90, v87
	v_fmac_f32_e32 v69, 0x31dc9c88, v65
	v_sin_f32_e32 v65, v69
	v_cos_f32_e32 v69, v69
	v_mul_f32_e32 v88, v73, v80
	v_mul_f32_e32 v94, v75, v80
	v_mov_b32_e32 v80, v83
	v_mul_f32_e32 v86, v75, v82
	v_mul_f32_e32 v96, v73, v82
	v_pk_mul_f32 v[82:83], v[90:91], v[80:81]
	v_pk_mul_f32 v[70:71], v[64:65], v[66:67]
	v_mov_b32_e32 v87, v82
	v_mov_b32_e32 v89, v83
	v_mov_b32_e32 v82, v91
	v_mov_b32_e32 v83, v90
	v_pk_mul_f32 v[80:81], v[82:83], v[80:81]
	v_pk_mul_f32 v[66:67], v[68:69], v[66:67]
	v_mov_b32_e32 v97, v80
	v_mov_b32_e32 v95, v81
	v_pk_fma_f32 v[68:69], v[68:69], v[78:79], v[70:71] neg_lo:[0,0,1] neg_hi:[0,0,1]
	v_pk_add_f32 v[82:83], v[86:87], v[88:89] neg_lo:[0,1] neg_hi:[0,1]
	v_pk_fma_f32 v[66:67], v[64:65], v[78:79], v[66:67]
	v_pk_add_f32 v[80:81], v[96:97], v[94:95]
	v_mov_b32_e32 v78, v68
	v_mov_b32_e32 v79, v69

.LBB0_1282:
	s_nop 0
	v_or_b32_e32 v49, 32, v168
	v_lshlrev_b32_e32 v50, 1, v49
	v_mov_b32_e32 v51, v169
	v_lshl_add_u64 v[50:51], v[50:51], 2, s[22:23]
	v_mov_b32_e32 v48, v243
	s_nop 0
	v_mov_b32_e32 v50, v246
	v_fmamk_f32 v48, v48, 0x3aaaaaab, v174
	v_mul_f32_e32 v51, 0x4b800000, v48
	v_cmp_gt_f32_e32 vcc, s79, v48
	s_nop 0
	v_cvt_f32_i32_e32 v56, v50
	v_cndmask_b32_e32 v48, v48, v51, vcc
	v_rsq_f32_e32 v48, v48
	s_nop 0
	v_mul_f32_e32 v50, 0x45800000, v48
	v_cndmask_b32_e32 v48, v48, v50, vcc
	v_pk_mul_f32 v[54:55], v[46:47], v[48:49] op_sel_hi:[1,0]
	v_pk_mul_f32 v[50:51], v[44:45], v[48:49] op_sel_hi:[1,0]
	v_pk_mul_f32 v[52:53], v[42:43], v[48:49] op_sel_hi:[1,0]
	v_pk_mul_f32 v[42:43], v[40:41], v[48:49] op_sel_hi:[1,0]
	s_and_saveexec_b64 s[76:77], s[6:7]
	s_cbranch_execz .LBB0_1284
	v_mul_f32_e32 v40, 0xbf549a78, v107
	v_cmp_gt_f32_e32 vcc, s86, v40
	v_cvt_f32_ubyte0_e32 v44, v108
	v_mul_f32_e32 v45, 0xbf549a78, v44
	v_cndmask_b32_e32 v41, 0, v180, vcc
	v_fmac_f32_e32 v41, 0xbf549a78, v107
	v_exp_f32_e32 v41, v41
	v_cndmask_b32_e32 v40, 0, v179, vcc
	v_cmp_gt_f32_e32 vcc, s86, v45
	v_cvt_f32_ubyte0_e32 v46, v105
	v_ldexp_f32 v40, v41, v40
	v_mul_f32_e32 v40, v40, v56
	v_mul_f32_e32 v41, 0.15915494, v40
	v_rndne_f32_e32 v41, v41
	v_fma_f32 v41, v40, 0.15915494, -v41
	v_fmac_f32_e32 v41, 0x31dc9c88, v40
	v_cndmask_b32_e32 v40, 0, v180, vcc
	v_fmac_f32_e32 v40, 0xbf549a78, v44
	v_mul_f32_e32 v47, 0xbf549a78, v46
	v_exp_f32_e32 v45, v40
	v_sin_f32_e32 v40, v41
	v_cos_f32_e32 v44, v41
	v_cndmask_b32_e32 v41, 0, v179, vcc
	v_cmp_gt_f32_e32 vcc, s86, v47
	v_ldexp_f32 v41, v45, v41
	v_mul_f32_e32 v41, v41, v56
	v_cndmask_b32_e32 v47, 0, v180, vcc
	v_fmac_f32_e32 v47, 0xbf549a78, v46
	v_exp_f32_e32 v57, v47
	v_cndmask_b32_e32 v58, 0, v179, vcc
	v_mul_f32_e32 v45, 0.15915494, v41
	v_rndne_f32_e32 v45, v45
	v_ldexp_f32 v57, v57, v58
	v_mul_f32_e32 v57, v57, v56
	v_mul_f32_e32 v58, 0.15915494, v57
	v_rndne_f32_e32 v58, v58
	v_fma_f32 v58, v57, 0.15915494, -v58
	v_fmac_f32_e32 v58, 0x31dc9c88, v57
	v_sin_f32_e32 v57, v58
	v_cos_f32_e32 v59, v58
	v_cvt_f32_ubyte0_e32 v58, v106
	v_mul_f32_e32 v60, 0xbf549a78, v58
	v_cmp_gt_f32_e32 vcc, s86, v60
	v_fma_f32 v45, v41, 0.15915494, -v45
	v_fmac_f32_e32 v45, 0x31dc9c88, v41
	v_cndmask_b32_e32 v60, 0, v180, vcc
	v_fmac_f32_e32 v60, 0xbf549a78, v58
	v_exp_f32_e32 v61, v60
	v_cndmask_b32_e32 v62, 0, v179, vcc
	v_sin_f32_e32 v41, v45
	v_cos_f32_e32 v45, v45
	v_ldexp_f32 v61, v61, v62
	v_mul_f32_e32 v61, v61, v56
	v_mul_f32_e32 v62, 0.15915494, v61
	v_rndne_f32_e32 v62, v62
	v_fma_f32 v62, v61, 0.15915494, -v62
	v_fmac_f32_e32 v62, 0x31dc9c88, v61
	v_sin_f32_e32 v63, v62
	v_cos_f32_e32 v62, v62
	v_mul_f32_e32 v60, v57, v52
	v_mul_f32_e32 v64, v59, v52
	v_mov_b32_e32 v52, v55
	v_mul_f32_e32 v58, v59, v54
	v_mul_f32_e32 v66, v57, v54
	v_pk_mul_f32 v[54:55], v[62:63], v[52:53]
	v_pk_mul_f32 v[46:47], v[40:41], v[42:43]
	v_mov_b32_e32 v59, v54
	v_mov_b32_e32 v61, v55
	v_mov_b32_e32 v54, v63
	v_mov_b32_e32 v55, v62
	v_pk_mul_f32 v[52:53], v[54:55], v[52:53]
	v_pk_mul_f32 v[42:43], v[44:45], v[42:43]
	v_mov_b32_e32 v67, v52
	v_mov_b32_e32 v65, v53
	v_pk_fma_f32 v[44:45], v[44:45], v[50:51], v[46:47] neg_lo:[0,0,1] neg_hi:[0,0,1]
	v_pk_add_f32 v[54:55], v[58:59], v[60:61] neg_lo:[0,1] neg_hi:[0,1]
	v_pk_fma_f32 v[42:43], v[40:41], v[50:51], v[42:43]
	v_pk_add_f32 v[52:53], v[66:67], v[64:65]
	v_mov_b32_e32 v50, v44
	v_mov_b32_e32 v51, v45

.LBB0_1306:
	s_nop 0
	v_or_b32_e32 v25, 48, v168
	v_lshlrev_b32_e32 v168, 1, v25
	v_lshl_add_u64 v[26:27], v[168:169], 2, s[22:23]
	v_mov_b32_e32 v24, v244
	s_nop 0
	v_mov_b32_e32 v26, v247
	v_fmamk_f32 v24, v24, 0x3aaaaaab, v174
	v_mul_f32_e32 v27, 0x4b800000, v24
	v_cmp_gt_f32_e32 vcc, s79, v24
	s_nop 0
	v_cvt_f32_i32_e32 v32, v26
	v_cndmask_b32_e32 v24, v24, v27, vcc
	v_rsq_f32_e32 v24, v24
	s_nop 0
	v_mul_f32_e32 v26, 0x45800000, v24
	v_cndmask_b32_e32 v24, v24, v26, vcc
	v_pk_mul_f32 v[30:31], v[22:23], v[24:25] op_sel_hi:[1,0]
	v_pk_mul_f32 v[26:27], v[20:21], v[24:25] op_sel_hi:[1,0]
	v_pk_mul_f32 v[28:29], v[18:19], v[24:25] op_sel_hi:[1,0]
	v_pk_mul_f32 v[18:19], v[16:17], v[24:25] op_sel_hi:[1,0]
	s_and_saveexec_b64 s[76:77], s[6:7]
	s_cbranch_execz .LBB0_1308
	v_mul_f32_e32 v16, 0xbf549a78, v107
	v_cmp_gt_f32_e32 vcc, s86, v16
	v_cvt_f32_ubyte0_e32 v20, v108
	v_mul_f32_e32 v21, 0xbf549a78, v20
	v_cndmask_b32_e32 v17, 0, v180, vcc
	v_fmac_f32_e32 v17, 0xbf549a78, v107
	v_exp_f32_e32 v17, v17
	v_cndmask_b32_e32 v16, 0, v179, vcc
	v_cmp_gt_f32_e32 vcc, s86, v21
	v_cvt_f32_ubyte0_e32 v22, v105
	v_ldexp_f32 v16, v17, v16
	v_mul_f32_e32 v16, v16, v32
	v_mul_f32_e32 v17, 0.15915494, v16
	v_rndne_f32_e32 v17, v17
	v_fma_f32 v17, v16, 0.15915494, -v17
	v_fmac_f32_e32 v17, 0x31dc9c88, v16
	v_cndmask_b32_e32 v16, 0, v180, vcc
	v_fmac_f32_e32 v16, 0xbf549a78, v20
	v_mul_f32_e32 v23, 0xbf549a78, v22
	v_exp_f32_e32 v21, v16
	v_sin_f32_e32 v16, v17
	v_cos_f32_e32 v20, v17
	v_cndmask_b32_e32 v17, 0, v179, vcc
	v_cmp_gt_f32_e32 vcc, s86, v23
	v_ldexp_f32 v17, v21, v17
	v_mul_f32_e32 v17, v17, v32
	v_cndmask_b32_e32 v23, 0, v180, vcc
	v_fmac_f32_e32 v23, 0xbf549a78, v22
	v_exp_f32_e32 v33, v23
	v_cndmask_b32_e32 v34, 0, v179, vcc
	v_mul_f32_e32 v21, 0.15915494, v17
	v_rndne_f32_e32 v21, v21
	v_ldexp_f32 v33, v33, v34
	v_mul_f32_e32 v33, v33, v32
	v_mul_f32_e32 v34, 0.15915494, v33
	v_rndne_f32_e32 v34, v34
	v_fma_f32 v34, v33, 0.15915494, -v34
	v_fmac_f32_e32 v34, 0x31dc9c88, v33
	v_sin_f32_e32 v33, v34
	v_cos_f32_e32 v35, v34
	v_cvt_f32_ubyte0_e32 v34, v106
	v_mul_f32_e32 v36, 0xbf549a78, v34
	v_cmp_gt_f32_e32 vcc, s86, v36
	v_fma_f32 v21, v17, 0.15915494, -v21
	v_fmac_f32_e32 v21, 0x31dc9c88, v17
	v_cndmask_b32_e32 v36, 0, v180, vcc
	v_fmac_f32_e32 v36, 0xbf549a78, v34
	v_exp_f32_e32 v37, v36
	v_cndmask_b32_e32 v38, 0, v179, vcc
	v_sin_f32_e32 v17, v21
	v_cos_f32_e32 v21, v21
	v_ldexp_f32 v37, v37, v38
	v_mul_f32_e32 v37, v37, v32
	v_mul_f32_e32 v38, 0.15915494, v37
	v_rndne_f32_e32 v38, v38
	v_fma_f32 v38, v37, 0.15915494, -v38
	v_fmac_f32_e32 v38, 0x31dc9c88, v37
	v_sin_f32_e32 v39, v38
	v_cos_f32_e32 v38, v38
	v_mul_f32_e32 v36, v33, v28
	v_mul_f32_e32 v40, v35, v28
	v_mov_b32_e32 v28, v31
	v_mul_f32_e32 v34, v35, v30
	v_mul_f32_e32 v42, v33, v30
	v_pk_mul_f32 v[30:31], v[38:39], v[28:29]
	v_pk_mul_f32 v[22:23], v[16:17], v[18:19]
	v_mov_b32_e32 v35, v30
	v_mov_b32_e32 v37, v31
	v_mov_b32_e32 v30, v39
	v_mov_b32_e32 v31, v38
	v_pk_mul_f32 v[28:29], v[30:31], v[28:29]
	v_pk_mul_f32 v[18:19], v[20:21], v[18:19]
	v_mov_b32_e32 v43, v28
	v_mov_b32_e32 v41, v29
	v_pk_fma_f32 v[20:21], v[20:21], v[26:27], v[22:23] neg_lo:[0,0,1] neg_hi:[0,0,1]
	v_pk_add_f32 v[30:31], v[34:35], v[36:37] neg_lo:[0,1] neg_hi:[0,1]
	v_pk_fma_f32 v[18:19], v[16:17], v[26:27], v[18:19]
	v_pk_add_f32 v[28:29], v[42:43], v[40:41]
	v_mov_b32_e32 v26, v20
	v_mov_b32_e32 v27, v21

.LBB0_1557:
	s_or_b64 exec, exec, s[2:3]
	v_mov_b32_e32 v0, v198
	s_barrier
	s_nop 0
	v_readfirstlane_b32 s0, v0
	s_ashr_i32 s1, s0, 8
	s_add_i32 s0, s1, s79
	s_cmpk_gt_i32 s0, 0xfff
	s_cbranch_scc1 .LBB0_1560
	v_readlane_b32 s2, v240, 0
	v_readlane_b32 s3, v240, 1
	s_load_dwordx4 s[4:7], s[2:3], 0x88
	v_mbcnt_hi_u32_b32 v2, -1, v199
	s_lshl_b32 s1, s1, 2
	v_readlane_b32 s2, v240, 20
	v_and_b32_e32 v0, 64, v2
	s_add_i32 s1, s2, s1
	s_lshl_b32 s2, s60, 3
	v_mov_b32_e32 v1, 0
	v_add_u32_e32 v3, 64, v0
	v_xor_b32_e32 v4, 32, v2
	v_xor_b32_e32 v5, 16, v2
	v_xor_b32_e32 v6, 8, v2
	v_xor_b32_e32 v7, 4, v2
	v_xor_b32_e32 v8, 2, v2
	v_xor_b32_e32 v9, 1, v2
	v_mov_b32_e32 v10, 0x358637bd
	s_mov_b32 s3, 0x800000
	v_lshlrev_b32_e32 v64, 4, v198
	v_and_b32_e32 v64, 0x3f0, v64
	s_waitcnt lgkmcnt(0)
	global_load_dwordx4 v[68:71], v64, s[4:5]
	global_load_dwordx4 v[72:75], v64, s[4:5] offset:1024
	global_load_dwordx4 v[76:79], v64, s[4:5] offset:2048
	global_load_dwordx4 v[80:83], v64, s[4:5] offset:3072
.LBB0_1559:
	v_mov_b32_e32 v0, v198
	v_cmp_lt_i32_e32 vcc, v4, v3
	v_bfe_u32 v11, v0, 6, 2
	v_add_u32_e32 v12, s1, v11
	v_ashrrev_i32_e32 v13, 31, v12
	v_lshlrev_b32_e32 v0, 4, v0
	v_lshlrev_b64 v[12:13], 12, v[12:13]
	v_and_b32_e32 v0, 0x3f0, v0
	s_waitcnt lgkmcnt(0)
	v_lshl_add_u64 v[12:13], s[6:7], 0, v[12:13]
	v_lshl_add_u64 v[32:33], v[12:13], 0, v[0:1]
	global_load_dwordx4 v[12:15], v[32:33], off
	global_load_dwordx4 v[16:19], v[32:33], off offset:1024
	global_load_dwordx4 v[20:23], v[32:33], off offset:2048
	global_load_dwordx4 v[24:27], v[32:33], off offset:3072
	v_cndmask_b32_e32 v11, v2, v4, vcc
	v_cmp_lt_i32_e32 vcc, v5, v3
	v_lshlrev_b32_e32 v11, 2, v11
	s_add_i32 s0, s0, s83
	v_cndmask_b32_e32 v28, v2, v5, vcc
	v_cmp_lt_i32_e32 vcc, v6, v3
	v_lshlrev_b32_e32 v50, 2, v28
	s_add_i32 s1, s1, s2
	v_cndmask_b32_e32 v29, v2, v6, vcc
	v_cmp_lt_i32_e32 vcc, v7, v3
	v_lshlrev_b32_e32 v51, 2, v29
	s_cmpk_lt_i32 s0, 0x1000
	v_cndmask_b32_e32 v30, v2, v7, vcc
	v_cmp_lt_i32_e32 vcc, v8, v3
	v_lshlrev_b32_e32 v52, 2, v30
	s_waitcnt vmcnt(3)
	v_mov_b32_e32 v36, v13
	v_cndmask_b32_e32 v31, v2, v8, vcc
	v_lshlrev_b32_e32 v53, 2, v31
	v_cmp_lt_i32_e32 vcc, v9, v3
	s_waitcnt vmcnt(2)
	v_mov_b32_e32 v37, v17
	v_mov_b32_e32 v35, v16
	v_cndmask_b32_e32 v34, v2, v9, vcc
	v_lshlrev_b32_e32 v54, 2, v34
	v_mov_b32_e32 v34, v12
	s_waitcnt vmcnt(1)
	v_mov_b32_e32 v44, v21
	s_waitcnt vmcnt(0)
	v_mov_b32_e32 v45, v25
	v_pk_mul_f32 v[36:37], v[36:37], v[36:37]
	v_mov_b32_e32 v38, v14
	v_mov_b32_e32 v39, v18
	v_mov_b32_e32 v42, v20
	v_mov_b32_e32 v43, v24
	v_pk_mul_f32 v[44:45], v[44:45], v[44:45]
	v_pk_fma_f32 v[34:35], v[34:35], v[34:35], v[36:37]
	v_mov_b32_e32 v40, v15
	v_mov_b32_e32 v41, v19
	v_mov_b32_e32 v46, v22
	v_mov_b32_e32 v47, v26
	v_pk_fma_f32 v[36:37], v[42:43], v[42:43], v[44:45]
	v_pk_fma_f32 v[34:35], v[38:39], v[38:39], v[34:35]
	v_mov_b32_e32 v48, v23
	v_mov_b32_e32 v49, v27
	v_pk_fma_f32 v[36:37], v[46:47], v[46:47], v[36:37]
	v_pk_fma_f32 v[34:35], v[40:41], v[40:41], v[34:35]
	v_pk_fma_f32 v[36:37], v[48:49], v[48:49], v[36:37]
	v_add_f32_e32 v34, v34, v35
	v_add_f32_e32 v34, v34, v36
	v_add_f32_e32 v34, v34, v37
	ds_bpermute_b32 v11, v11, v34
	s_waitcnt lgkmcnt(0)
	v_add_f32_e32 v11, v34, v11
	ds_bpermute_b32 v34, v50, v11
	s_waitcnt lgkmcnt(0)
	v_add_f32_e32 v11, v11, v34
	ds_bpermute_b32 v34, v51, v11
	s_waitcnt lgkmcnt(0)
	v_add_f32_e32 v11, v11, v34
	ds_bpermute_b32 v34, v52, v11
	s_waitcnt lgkmcnt(0)
	v_add_f32_e32 v11, v11, v34
	ds_bpermute_b32 v34, v53, v11
	s_waitcnt lgkmcnt(0)
	v_add_f32_e32 v11, v11, v34
	ds_bpermute_b32 v34, v54, v11
	s_waitcnt lgkmcnt(0)
	v_add_f32_e32 v11, v11, v34
	v_fmamk_f32 v11, v11, 0x3a800000, v10
	v_mul_f32_e32 v34, 0x4b800000, v11
	v_cmp_gt_f32_e32 vcc, s3, v11
	s_nop 1
	v_cndmask_b32_e32 v11, v11, v34, vcc
	v_rsq_f32_e32 v11, v11
	s_nop 0
	v_mul_f32_e32 v34, 0x45800000, v11
	v_cndmask_b32_e32 v34, v11, v34, vcc
	v_pk_mul_f32 v[12:13], v[12:13], v[34:35] op_sel_hi:[1,0]
	v_pk_mul_f32 v[14:15], v[14:15], v[34:35] op_sel_hi:[1,0]
	v_pk_mul_f32 v[12:13], v[68:69], v[12:13]
	v_pk_mul_f32 v[14:15], v[70:71], v[14:15]
	global_store_dwordx4 v[32:33], v[12:15], off
	v_pk_mul_f32 v[18:19], v[18:19], v[34:35] op_sel_hi:[1,0]
	v_pk_mul_f32 v[16:17], v[16:17], v[34:35] op_sel_hi:[1,0]
	v_pk_mul_f32 v[14:15], v[74:75], v[18:19]
	v_pk_mul_f32 v[12:13], v[72:73], v[16:17]
	global_store_dwordx4 v[32:33], v[12:15], off offset:1024
	v_pk_mul_f32 v[16:17], v[22:23], v[34:35] op_sel_hi:[1,0]
	v_pk_mul_f32 v[18:19], v[20:21], v[34:35] op_sel_hi:[1,0]
	v_pk_mul_f32 v[14:15], v[78:79], v[16:17]
	v_pk_mul_f32 v[12:13], v[76:77], v[18:19]
	global_store_dwordx4 v[32:33], v[12:15], off offset:2048
	v_pk_mul_f32 v[16:17], v[26:27], v[34:35] op_sel_hi:[1,0]
	v_pk_mul_f32 v[18:19], v[24:25], v[34:35] op_sel_hi:[1,0]
	v_pk_mul_f32 v[14:15], v[82:83], v[16:17]
	v_pk_mul_f32 v[12:13], v[80:81], v[18:19]
	global_store_dwordx4 v[32:33], v[12:15], off offset:3072
	s_cbranch_scc1 .LBB0_1559
